# EpiG2 rope-table loads software-pipelined by one row block; G1 k_rope table loads prefetched ahead of previous block stores
# baseline (speedup 1.0000x reference)
; #define GAS __attribute__((address_space(1)))
; DI u32x4 pack8(const f32x4 a, const f32x4 b) { return (u32x4){pk2(a.x, a.y), pk2(a.z, a.w), pk2(b.x, b.y), pk2(b.z, b.w)}; }
;   DI void operator()(const acc_t& acc, const Unit& u, int, int, int, int) const {
;     ...
;       if (part == 1 && wc == 0) {
;         const GAS float* tab = (const GAS float*)(ws_ + OFF_ROPE);
;         GAS float* okr = out_ + (samp ? O_KRS : O_KRP);
;         GAS u16* kr = (GAS u16*)(ws_ + OFF_KROPE);
;         const int i0 = (8 * fq) & 15;
; #pragma unroll
;         for (int ai = 0; ai < 2; ++ai)
; #pragma unroll
;           for (int m = 0; m < 4; ++m) {
;             const int row = row0 + ai * 128 + m * 16, rl = rl0 + ai * 128 + m * 16;
;             const int ridx = samp ? 2048 + (rl & 63) : (rl & 2047);
;             f32x4 o[2];
; #pragma unroll
;             for (int n = 0; n < 2; ++n) {
;               const f32x4 cs = *(const GAS f32x4*)(tab + ridx * 32 + i0 + 4 * n), sn = *(const GAS f32x4*)(tab + ridx * 32 + 16 + i0 + 4 * n);
;               const f32x4 mine = acc[ai][1][m][n];
;               f32x4 oth; oth.x = __shfl_xor(mine.x, 32); oth.y = __shfl_xor(mine.y, 32); oth.z = __shfl_xor(mine.z, 32); oth.w = __shfl_xor(mine.w, 32);
;               o[n] = (fq < 2) ? (mine * cs - oth * sn) : (mine * cs + oth * sn);
;             }
;             *(GAS f32x4*)(okr + (size_t)rl * 32 + 8 * fq) = o[0]; *(GAS f32x4*)(okr + (size_t)rl * 32 + 8 * fq + 4) = o[1];
;             *(GAS u32x4*)(kr + (size_t)row * 32 + 8 * fq) = pack8(o[0], o[1]);
;           }
;       }
.LBB0_247:
	s_cmp_lg_u32 s51, 0
	s_cselect_b64 s[4:5], -1, 0
	s_cmp_lg_u32 s21, 1
	s_cselect_b64 s[20:21], -1, 0
	s_or_b64 s[4:5], s[20:21], s[4:5]
	s_and_b64 vcc, exec, s[4:5]
	s_cbranch_vccnz .LBB0_249
	s_add_u32 s4, s64, 0x90100
	s_addc_u32 s5, s65, 0
	s_and_b64 s[20:21], s[6:7], exec
	s_mov_b32 s20, 0x25100000
	s_cselect_b32 s20, s20, 0x24400000
	s_add_u32 s20, s66, s20
	v_and_b32_e32 v139, 15, v166
	s_addc_u32 s21, s67, 0
	v_lshlrev_b32_e32 v154, 2, v194
	v_or_b32_e32 v131, 0x800, v139
	v_and_b32_e32 v141, 0x7cf, v164
	v_lshl_add_u64 v[132:133], s[20:21], 0, v[154:155]
	v_lshlrev_b32_e32 v154, 1, v194
	v_cndmask_b32_e64 v141, v141, v131, s[6:7]
	v_and_b32_e32 v135, 8, v194
	v_lshl_add_u64 v[136:137], s[64:65], 0, v[154:155]
	v_lshlrev_b32_e32 v154, 7, v141
	v_lshl_add_u64 v[172:173], s[4:5], 0, v[154:155]
	v_lshlrev_b32_e32 v154, 2, v135
	v_lshl_add_u64 v[184:185], v[172:173], 0, v[154:155]
	global_load_dwordx4 v[172:175], v[184:185], off offset:64
	global_load_dwordx4 v[176:179], v[184:185], off offset:80
	global_load_dwordx4 v[180:183], v[184:185], off
	global_load_dwordx4 v[194:197], v[184:185], off offset:16
	ds_bpermute_b32 v184, v170, v118
	ds_bpermute_b32 v185, v170, v119
	ds_bpermute_b32 v198, v170, v120
	ds_bpermute_b32 v199, v170, v121
	ds_bpermute_b32 v200, v170, v110
	ds_bpermute_b32 v201, v170, v111
	ds_bpermute_b32 v202, v170, v112
	ds_bpermute_b32 v203, v170, v113
	s_movk_i32 s51, 0x7ff
	v_bitop3_b32 v141, v166, s51, 16 bitop3:0xc8
	v_or_b32_e32 v135, 0x810, v139
	v_ashrrev_i32_e32 v167, 31, v166
	v_cndmask_b32_e64 v141, v141, v135, s[6:7]
	v_lshlrev_b64 v[204:205], 6, v[164:165]
	v_lshlrev_b64 v[208:209], 7, v[166:167]
	v_lshlrev_b32_e32 v206, 7, v141
	v_cmp_gt_u32_e32 vcc, 2, v193
	s_mov_b64 s[20:21], 0x24428100
	v_mov_b32_e32 v207, v155
	v_lshl_add_u64 v[208:209], v[132:133], 0, v[208:209]
	v_lshl_add_u64 v[136:137], v[136:137], 0, s[20:21]
	v_lshl_add_u64 v[206:207], s[4:5], 0, v[206:207]
	v_lshl_add_u64 v[204:205], v[136:137], 0, v[204:205]
	v_lshl_add_u64 v[206:207], v[206:207], 0, v[154:155]
	s_waitcnt vmcnt(3) lgkmcnt(4)
	v_pk_mul_f32 v[174:175], v[174:175], v[198:199]
	v_pk_mul_f32 v[172:173], v[172:173], v[184:185]
	s_waitcnt vmcnt(2) lgkmcnt(0)
	v_pk_mul_f32 v[178:179], v[178:179], v[202:203]
	v_pk_mul_f32 v[176:177], v[176:177], v[200:201]
	v_xor_b32_e32 v141, 0x80000000, v172
	v_xor_b32_e32 v143, 0x80000000, v173
	v_xor_b32_e32 v145, 0x80000000, v174
	v_xor_b32_e32 v165, 0x80000000, v175
	v_xor_b32_e32 v167, 0x80000000, v176
	v_xor_b32_e32 v169, 0x80000000, v177
	v_xor_b32_e32 v171, 0x80000000, v178
	v_xor_b32_e32 v184, 0x80000000, v179
	v_cndmask_b32_e32 v175, v175, v165, vcc
	v_cndmask_b32_e32 v174, v174, v145, vcc
	v_cndmask_b32_e32 v173, v173, v143, vcc
	v_cndmask_b32_e32 v172, v172, v141, vcc
	v_cndmask_b32_e32 v179, v179, v184, vcc
	v_cndmask_b32_e32 v178, v178, v171, vcc
	v_cndmask_b32_e32 v177, v177, v169, vcc
	v_cndmask_b32_e32 v176, v176, v167, vcc
	s_waitcnt vmcnt(1)
	v_pk_fma_f32 v[172:173], v[118:119], v[180:181], v[172:173]
	v_pk_fma_f32 v[174:175], v[120:121], v[182:183], v[174:175]
	s_waitcnt vmcnt(0)
	v_pk_fma_f32 v[176:177], v[110:111], v[194:195], v[176:177]
	v_pk_fma_f32 v[178:179], v[112:113], v[196:197], v[178:179]
	global_load_dwordx4 v[232:235], v[206:207], off offset:64
	global_load_dwordx4 v[236:239], v[206:207], off offset:80
	global_load_dwordx4 v[240:243], v[206:207], off
	global_load_dwordx4 v[244:247], v[206:207], off offset:16
	global_store_dwordx4 v[208:209], v[172:175], off
	global_store_dwordx4 v[208:209], v[176:179], off offset:16
	ds_bpermute_b32 v198, v170, v102
	v_cvt_pk_bf16_f32 v172, v172, v173
	v_cvt_pk_bf16_f32 v173, v174, v175
	v_cvt_pk_bf16_f32 v174, v176, v177
	v_cvt_pk_bf16_f32 v175, v178, v179
	global_store_dwordx4 v[204:205], v[172:175], off
	s_waitcnt vmcnt(3)
	v_mov_b32_e32 v172, v232
	v_mov_b32_e32 v173, v233
	v_mov_b32_e32 v174, v234
	v_mov_b32_e32 v175, v235
	v_mov_b32_e32 v176, v236
	v_mov_b32_e32 v177, v237
	v_mov_b32_e32 v178, v238
	v_mov_b32_e32 v179, v239
	v_mov_b32_e32 v180, v240
	v_mov_b32_e32 v181, v241
	v_mov_b32_e32 v182, v242
	v_mov_b32_e32 v183, v243
	v_mov_b32_e32 v194, v244
	v_mov_b32_e32 v195, v245
	v_mov_b32_e32 v196, v246
	v_mov_b32_e32 v197, v247
	ds_bpermute_b32 v199, v170, v103
	ds_bpermute_b32 v200, v170, v104
	ds_bpermute_b32 v201, v170, v105
	ds_bpermute_b32 v202, v170, v94
	ds_bpermute_b32 v203, v170, v95
	ds_bpermute_b32 v204, v170, v96
	ds_bpermute_b32 v205, v170, v97
	v_bitop3_b32 v141, v166, s51, 32 bitop3:0xc8
	v_or_b32_e32 v165, 0x820, v139
	v_or_b32_e32 v184, 16, v166
	v_cndmask_b32_e64 v141, v141, v165, s[6:7]
	v_ashrrev_i32_e32 v185, 31, v184
	v_lshlrev_b32_e32 v206, 7, v141
	v_ashrrev_i32_e32 v169, 31, v168
	v_lshlrev_b64 v[184:185], 7, v[184:185]
	v_mov_b32_e32 v207, v155
	v_lshlrev_b64 v[168:169], 6, v[168:169]
	v_lshl_add_u64 v[184:185], v[132:133], 0, v[184:185]
	v_lshl_add_u64 v[206:207], s[4:5], 0, v[206:207]
	v_lshl_add_u64 v[168:169], v[136:137], 0, v[168:169]
	v_lshl_add_u64 v[206:207], v[206:207], 0, v[154:155]
	s_waitcnt lgkmcnt(4)
	v_pk_mul_f32 v[174:175], v[174:175], v[200:201]
	v_pk_mul_f32 v[172:173], v[172:173], v[198:199]
	s_waitcnt lgkmcnt(0)
; #define GAS __attribute__((address_space(1)))
; DI u32x4 pack8(const f32x4 a, const f32x4 b) { return (u32x4){pk2(a.x, a.y), pk2(a.z, a.w), pk2(b.x, b.y), pk2(b.z, b.w)}; }
;   DI void operator()(const acc_t& acc, const Unit& u, int, int, int, int) const {
;     ...
;       if (part == 1 && wc == 0) {
;         const GAS float* tab = (const GAS float*)(ws_ + OFF_ROPE);
;         GAS float* okr = out_ + (samp ? O_KRS : O_KRP);
;         GAS u16* kr = (GAS u16*)(ws_ + OFF_KROPE);
;         const int i0 = (8 * fq) & 15;
; #pragma unroll
;         for (int ai = 0; ai < 2; ++ai)
; #pragma unroll
;           for (int m = 0; m < 4; ++m) {
;             const int row = row0 + ai * 128 + m * 16, rl = rl0 + ai * 128 + m * 16;
;             const int ridx = samp ? 2048 + (rl & 63) : (rl & 2047);
;             f32x4 o[2];
; #pragma unroll
;             for (int n = 0; n < 2; ++n) {
;               const f32x4 cs = *(const GAS f32x4*)(tab + ridx * 32 + i0 + 4 * n), sn = *(const GAS f32x4*)(tab + ridx * 32 + 16 + i0 + 4 * n);
;               const f32x4 mine = acc[ai][1][m][n];
;               f32x4 oth; oth.x = __shfl_xor(mine.x, 32); oth.y = __shfl_xor(mine.y, 32); oth.z = __shfl_xor(mine.z, 32); oth.w = __shfl_xor(mine.w, 32);
;               o[n] = (fq < 2) ? (mine * cs - oth * sn) : (mine * cs + oth * sn);
;             }
;             *(GAS f32x4*)(okr + (size_t)rl * 32 + 8 * fq) = o[0]; *(GAS f32x4*)(okr + (size_t)rl * 32 + 8 * fq + 4) = o[1];
;             *(GAS u32x4*)(kr + (size_t)row * 32 + 8 * fq) = pack8(o[0], o[1]);
;           }
;       }
	v_pk_mul_f32 v[178:179], v[178:179], v[204:205]
	v_pk_mul_f32 v[176:177], v[176:177], v[202:203]
	v_xor_b32_e32 v141, 0x80000000, v172
	v_xor_b32_e32 v143, 0x80000000, v173
	v_xor_b32_e32 v145, 0x80000000, v174
	v_xor_b32_e32 v167, 0x80000000, v175
	v_xor_b32_e32 v171, 0x80000000, v176
	v_xor_b32_e32 v193, 0x80000000, v177
	v_xor_b32_e32 v198, 0x80000000, v178
	v_xor_b32_e32 v199, 0x80000000, v179
	v_cndmask_b32_e32 v175, v175, v167, vcc
	v_cndmask_b32_e32 v174, v174, v145, vcc
	v_cndmask_b32_e32 v173, v173, v143, vcc
	v_cndmask_b32_e32 v172, v172, v141, vcc
	v_cndmask_b32_e32 v179, v179, v199, vcc
	v_cndmask_b32_e32 v178, v178, v198, vcc
	v_cndmask_b32_e32 v177, v177, v193, vcc
	v_cndmask_b32_e32 v176, v176, v171, vcc
	s_nop 0
	v_pk_fma_f32 v[172:173], v[102:103], v[180:181], v[172:173]
	v_pk_fma_f32 v[174:175], v[104:105], v[182:183], v[174:175]
	s_nop 0
	v_pk_fma_f32 v[176:177], v[94:95], v[194:195], v[176:177]
	v_pk_fma_f32 v[178:179], v[96:97], v[196:197], v[178:179]
	global_load_dwordx4 v[232:235], v[206:207], off offset:64
	global_load_dwordx4 v[236:239], v[206:207], off offset:80
	global_load_dwordx4 v[240:243], v[206:207], off
	global_load_dwordx4 v[244:247], v[206:207], off offset:16
	global_store_dwordx4 v[184:185], v[172:175], off
	global_store_dwordx4 v[184:185], v[176:179], off offset:16
	ds_bpermute_b32 v184, v170, v86
	v_cvt_pk_bf16_f32 v172, v172, v173
	v_cvt_pk_bf16_f32 v173, v174, v175
	v_cvt_pk_bf16_f32 v174, v176, v177
	v_cvt_pk_bf16_f32 v175, v178, v179
	global_store_dwordx4 v[168:169], v[172:175], off
	s_waitcnt vmcnt(3)
	v_mov_b32_e32 v172, v232
	v_mov_b32_e32 v173, v233
	v_mov_b32_e32 v174, v234
	v_mov_b32_e32 v175, v235
	v_mov_b32_e32 v176, v236
	v_mov_b32_e32 v177, v237
	v_mov_b32_e32 v178, v238
	v_mov_b32_e32 v179, v239
	v_mov_b32_e32 v180, v240
	v_mov_b32_e32 v181, v241
	v_mov_b32_e32 v182, v242
	v_mov_b32_e32 v183, v243
	v_mov_b32_e32 v194, v244
	v_mov_b32_e32 v195, v245
	v_mov_b32_e32 v196, v246
	v_mov_b32_e32 v197, v247
	ds_bpermute_b32 v185, v170, v87
	ds_bpermute_b32 v198, v170, v88
	ds_bpermute_b32 v199, v170, v89
	ds_bpermute_b32 v200, v170, v78
	ds_bpermute_b32 v201, v170, v79
	ds_bpermute_b32 v202, v170, v80
	ds_bpermute_b32 v203, v170, v81
	v_ashrrev_i32_e32 v145, 31, v144
	v_bitop3_b32 v141, v166, s51, 48 bitop3:0xc8
	v_lshlrev_b64 v[206:207], 6, v[144:145]
	v_or_b32_e32 v144, 0x830, v139
	v_or_b32_e32 v168, 32, v166
	v_cndmask_b32_e64 v139, v141, v144, s[6:7]
	v_ashrrev_i32_e32 v169, 31, v168
	v_lshlrev_b32_e32 v204, 7, v139
	v_lshlrev_b64 v[168:169], 7, v[168:169]
	v_mov_b32_e32 v205, v155
	v_lshl_add_u64 v[168:169], v[132:133], 0, v[168:169]
	v_lshl_add_u64 v[204:205], s[4:5], 0, v[204:205]
	v_lshl_add_u64 v[206:207], v[136:137], 0, v[206:207]
	v_lshl_add_u64 v[204:205], v[204:205], 0, v[154:155]
	s_waitcnt lgkmcnt(4)
	v_pk_mul_f32 v[174:175], v[174:175], v[198:199]
	v_pk_mul_f32 v[172:173], v[172:173], v[184:185]
	s_waitcnt lgkmcnt(0)
	v_pk_mul_f32 v[178:179], v[178:179], v[202:203]
	v_pk_mul_f32 v[176:177], v[176:177], v[200:201]
	v_xor_b32_e32 v139, 0x80000000, v172
	v_xor_b32_e32 v141, 0x80000000, v173
	v_xor_b32_e32 v143, 0x80000000, v174
	v_xor_b32_e32 v145, 0x80000000, v175
	v_xor_b32_e32 v167, 0x80000000, v176
	v_xor_b32_e32 v171, 0x80000000, v177
	v_xor_b32_e32 v184, 0x80000000, v178
	v_xor_b32_e32 v185, 0x80000000, v179
	v_cndmask_b32_e32 v175, v175, v145, vcc
	v_cndmask_b32_e32 v174, v174, v143, vcc
	v_cndmask_b32_e32 v173, v173, v141, vcc
	v_cndmask_b32_e32 v172, v172, v139, vcc
	v_cndmask_b32_e32 v179, v179, v185, vcc
	v_cndmask_b32_e32 v178, v178, v184, vcc
	v_cndmask_b32_e32 v177, v177, v171, vcc
	v_cndmask_b32_e32 v176, v176, v167, vcc
	s_nop 0
	v_pk_fma_f32 v[172:173], v[86:87], v[180:181], v[172:173]
	v_pk_fma_f32 v[174:175], v[88:89], v[182:183], v[174:175]
	s_nop 0
	v_pk_fma_f32 v[176:177], v[78:79], v[194:195], v[176:177]
	v_pk_fma_f32 v[178:179], v[80:81], v[196:197], v[178:179]
	global_load_dwordx4 v[232:235], v[204:205], off offset:64
	global_load_dwordx4 v[236:239], v[204:205], off offset:80
	global_load_dwordx4 v[240:243], v[204:205], off
	global_load_dwordx4 v[244:247], v[204:205], off offset:16
	global_store_dwordx4 v[168:169], v[172:175], off
	global_store_dwordx4 v[168:169], v[176:179], off offset:16
	ds_bpermute_b32 v184, v170, v70
	v_cvt_pk_bf16_f32 v172, v172, v173
	v_cvt_pk_bf16_f32 v173, v174, v175
	v_cvt_pk_bf16_f32 v174, v176, v177
	v_cvt_pk_bf16_f32 v175, v178, v179
	global_store_dwordx4 v[206:207], v[172:175], off
	s_waitcnt vmcnt(3)
	v_mov_b32_e32 v172, v232
	v_mov_b32_e32 v173, v233
	v_mov_b32_e32 v174, v234
	v_mov_b32_e32 v175, v235
	v_mov_b32_e32 v176, v236
	v_mov_b32_e32 v177, v237
	v_mov_b32_e32 v178, v238
	v_mov_b32_e32 v179, v239
	v_mov_b32_e32 v180, v240
	v_mov_b32_e32 v181, v241
	v_mov_b32_e32 v182, v242
	v_mov_b32_e32 v183, v243
	v_mov_b32_e32 v194, v244
	v_mov_b32_e32 v195, v245
	v_mov_b32_e32 v196, v246
	v_mov_b32_e32 v197, v247
	ds_bpermute_b32 v185, v170, v71
	ds_bpermute_b32 v198, v170, v72
	ds_bpermute_b32 v199, v170, v73
	ds_bpermute_b32 v200, v170, v66
	ds_bpermute_b32 v201, v170, v67
	ds_bpermute_b32 v202, v170, v68
	ds_bpermute_b32 v203, v170, v69
	v_add_u32_e32 v204, 0x80, v166
	v_and_b32_e32 v139, 0x7ff, v204
	v_or_b32_e32 v168, 48, v166
	v_cndmask_b32_e64 v131, v139, v131, s[6:7]
	v_ashrrev_i32_e32 v169, 31, v168
	v_lshlrev_b32_e32 v206, 7, v131
	v_ashrrev_i32_e32 v143, 31, v142
	v_lshlrev_b64 v[168:169], 7, v[168:169]
	v_mov_b32_e32 v207, v155
	v_lshlrev_b64 v[142:143], 6, v[142:143]
	v_lshl_add_u64 v[168:169], v[132:133], 0, v[168:169]
	v_lshl_add_u64 v[206:207], s[4:5], 0, v[206:207]
	v_lshl_add_u64 v[142:143], v[136:137], 0, v[142:143]
	v_lshl_add_u64 v[206:207], v[206:207], 0, v[154:155]
	v_ashrrev_i32_e32 v205, 31, v204
	v_lshlrev_b64 v[204:205], 7, v[204:205]
	v_lshl_add_u64 v[204:205], v[132:133], 0, v[204:205]
	s_waitcnt lgkmcnt(4)
; #define GAS __attribute__((address_space(1)))
; DI u32x4 pack8(const f32x4 a, const f32x4 b) { return (u32x4){pk2(a.x, a.y), pk2(a.z, a.w), pk2(b.x, b.y), pk2(b.z, b.w)}; }
;   DI void operator()(const acc_t& acc, const Unit& u, int, int, int, int) const {
;     ...
;       if (part == 1 && wc == 0) {
;         const GAS float* tab = (const GAS float*)(ws_ + OFF_ROPE);
;         GAS float* okr = out_ + (samp ? O_KRS : O_KRP);
;         GAS u16* kr = (GAS u16*)(ws_ + OFF_KROPE);
;         const int i0 = (8 * fq) & 15;
; #pragma unroll
;         for (int ai = 0; ai < 2; ++ai)
; #pragma unroll
;           for (int m = 0; m < 4; ++m) {
;             const int row = row0 + ai * 128 + m * 16, rl = rl0 + ai * 128 + m * 16;
;             const int ridx = samp ? 2048 + (rl & 63) : (rl & 2047);
;             f32x4 o[2];
; #pragma unroll
;             for (int n = 0; n < 2; ++n) {
;               const f32x4 cs = *(const GAS f32x4*)(tab + ridx * 32 + i0 + 4 * n), sn = *(const GAS f32x4*)(tab + ridx * 32 + 16 + i0 + 4 * n);
;               const f32x4 mine = acc[ai][1][m][n];
;               f32x4 oth; oth.x = __shfl_xor(mine.x, 32); oth.y = __shfl_xor(mine.y, 32); oth.z = __shfl_xor(mine.z, 32); oth.w = __shfl_xor(mine.w, 32);
;               o[n] = (fq < 2) ? (mine * cs - oth * sn) : (mine * cs + oth * sn);
;             }
;             *(GAS f32x4*)(okr + (size_t)rl * 32 + 8 * fq) = o[0]; *(GAS f32x4*)(okr + (size_t)rl * 32 + 8 * fq + 4) = o[1];
;             *(GAS u32x4*)(kr + (size_t)row * 32 + 8 * fq) = pack8(o[0], o[1]);
;           }
;       }
	v_pk_mul_f32 v[174:175], v[174:175], v[198:199]
	v_pk_mul_f32 v[172:173], v[172:173], v[184:185]
	s_waitcnt lgkmcnt(0)
	v_pk_mul_f32 v[178:179], v[178:179], v[202:203]
	v_pk_mul_f32 v[176:177], v[176:177], v[200:201]
	v_xor_b32_e32 v131, 0x80000000, v172
	v_xor_b32_e32 v139, 0x80000000, v173
	v_xor_b32_e32 v141, 0x80000000, v174
	v_xor_b32_e32 v145, 0x80000000, v175
	v_xor_b32_e32 v167, 0x80000000, v176
	v_xor_b32_e32 v171, 0x80000000, v177
	v_xor_b32_e32 v184, 0x80000000, v178
	v_xor_b32_e32 v185, 0x80000000, v179
	v_cndmask_b32_e32 v175, v175, v145, vcc
	v_cndmask_b32_e32 v174, v174, v141, vcc
	v_cndmask_b32_e32 v173, v173, v139, vcc
	v_cndmask_b32_e32 v172, v172, v131, vcc
	v_cndmask_b32_e32 v179, v179, v185, vcc
	v_cndmask_b32_e32 v178, v178, v184, vcc
	v_cndmask_b32_e32 v177, v177, v171, vcc
	v_cndmask_b32_e32 v176, v176, v167, vcc
	s_nop 0
	v_pk_fma_f32 v[172:173], v[70:71], v[180:181], v[172:173]
	v_pk_fma_f32 v[174:175], v[72:73], v[182:183], v[174:175]
	s_nop 0
	v_pk_fma_f32 v[176:177], v[66:67], v[194:195], v[176:177]
	v_pk_fma_f32 v[178:179], v[68:69], v[196:197], v[178:179]
	global_load_dwordx4 v[232:235], v[206:207], off offset:64
	global_load_dwordx4 v[236:239], v[206:207], off offset:80
	global_load_dwordx4 v[240:243], v[206:207], off
	global_load_dwordx4 v[244:247], v[206:207], off offset:16
	global_store_dwordx4 v[168:169], v[172:175], off
	global_store_dwordx4 v[168:169], v[176:179], off offset:16
	ds_bpermute_b32 v168, v170, v52
	v_cvt_pk_bf16_f32 v172, v172, v173
	v_cvt_pk_bf16_f32 v173, v174, v175
	v_cvt_pk_bf16_f32 v174, v176, v177
	v_cvt_pk_bf16_f32 v175, v178, v179
	global_store_dwordx4 v[142:143], v[172:175], off
	s_waitcnt vmcnt(3)
	v_mov_b32_e32 v172, v232
	v_mov_b32_e32 v173, v233
	v_mov_b32_e32 v174, v234
	v_mov_b32_e32 v175, v235
	v_mov_b32_e32 v176, v236
	v_mov_b32_e32 v177, v237
	v_mov_b32_e32 v178, v238
	v_mov_b32_e32 v179, v239
	v_mov_b32_e32 v180, v240
	v_mov_b32_e32 v181, v241
	v_mov_b32_e32 v182, v242
	v_mov_b32_e32 v183, v243
	v_mov_b32_e32 v194, v244
	v_mov_b32_e32 v195, v245
	v_mov_b32_e32 v196, v246
	v_mov_b32_e32 v197, v247
	ds_bpermute_b32 v142, v170, v50
	ds_bpermute_b32 v143, v170, v51
	ds_bpermute_b32 v169, v170, v53
	ds_bpermute_b32 v184, v170, v42
	ds_bpermute_b32 v185, v170, v43
	ds_bpermute_b32 v198, v170, v44
	ds_bpermute_b32 v199, v170, v45
	v_ashrrev_i32_e32 v141, 31, v140
	v_add_u32_e32 v200, 0x90, v166
	v_lshlrev_b64 v[140:141], 6, v[140:141]
	v_and_b32_e32 v131, 0x7ff, v200
	v_cndmask_b32_e64 v131, v131, v135, s[6:7]
	v_lshl_add_u64 v[206:207], v[136:137], 0, v[140:141]
	v_lshlrev_b32_e32 v202, 7, v131
	v_mov_b32_e32 v203, v155
	v_lshl_add_u64 v[202:203], s[4:5], 0, v[202:203]
	v_lshl_add_u64 v[202:203], v[202:203], 0, v[154:155]
	v_ashrrev_i32_e32 v201, 31, v200
	v_lshlrev_b64 v[200:201], 7, v[200:201]
	v_lshl_add_u64 v[200:201], v[132:133], 0, v[200:201]
	s_waitcnt lgkmcnt(4)
	v_pk_mul_f32 v[140:141], v[174:175], v[168:169]
	v_pk_mul_f32 v[142:143], v[172:173], v[142:143]
	s_waitcnt lgkmcnt(0)
	v_pk_mul_f32 v[168:169], v[178:179], v[198:199]
	v_pk_mul_f32 v[172:173], v[176:177], v[184:185]
	v_xor_b32_e32 v131, 0x80000000, v142
	v_xor_b32_e32 v135, 0x80000000, v143
	v_xor_b32_e32 v139, 0x80000000, v140
	v_xor_b32_e32 v145, 0x80000000, v141
	v_xor_b32_e32 v167, 0x80000000, v172
	v_xor_b32_e32 v171, 0x80000000, v173
	v_xor_b32_e32 v176, 0x80000000, v168
	v_xor_b32_e32 v177, 0x80000000, v169
	v_cndmask_b32_e32 v175, v141, v145, vcc
	v_cndmask_b32_e32 v174, v140, v139, vcc
	v_cndmask_b32_e32 v141, v143, v135, vcc
	v_cndmask_b32_e32 v140, v142, v131, vcc
	v_cndmask_b32_e32 v169, v169, v177, vcc
	v_cndmask_b32_e32 v168, v168, v176, vcc
	v_cndmask_b32_e32 v173, v173, v171, vcc
	v_cndmask_b32_e32 v172, v172, v167, vcc
	s_nop 0
	v_pk_fma_f32 v[140:141], v[50:51], v[180:181], v[140:141]
	v_pk_fma_f32 v[142:143], v[52:53], v[182:183], v[174:175]
	s_nop 0
	v_pk_fma_f32 v[172:173], v[42:43], v[194:195], v[172:173]
	v_pk_fma_f32 v[174:175], v[44:45], v[196:197], v[168:169]
	global_load_dwordx4 v[232:235], v[202:203], off offset:64
	global_load_dwordx4 v[236:239], v[202:203], off offset:80
	global_load_dwordx4 v[240:243], v[202:203], off
	global_load_dwordx4 v[244:247], v[202:203], off offset:16
	global_store_dwordx4 v[204:205], v[140:143], off
	global_store_dwordx4 v[204:205], v[172:175], off offset:16
	ds_bpermute_b32 v168, v170, v34
	v_cvt_pk_bf16_f32 v140, v140, v141
	v_cvt_pk_bf16_f32 v141, v142, v143
	v_cvt_pk_bf16_f32 v142, v172, v173
	v_cvt_pk_bf16_f32 v143, v174, v175
	global_store_dwordx4 v[206:207], v[140:143], off
	s_waitcnt vmcnt(3)
	v_mov_b32_e32 v140, v232
	v_mov_b32_e32 v141, v233
	v_mov_b32_e32 v142, v234
	v_mov_b32_e32 v143, v235
	v_mov_b32_e32 v172, v236
	v_mov_b32_e32 v173, v237
	v_mov_b32_e32 v174, v238
	v_mov_b32_e32 v175, v239
	v_mov_b32_e32 v176, v240
	v_mov_b32_e32 v177, v241
	v_mov_b32_e32 v178, v242
	v_mov_b32_e32 v179, v243
	v_mov_b32_e32 v180, v244
	v_mov_b32_e32 v181, v245
	v_mov_b32_e32 v182, v246
	v_mov_b32_e32 v183, v247
	ds_bpermute_b32 v169, v170, v35
	ds_bpermute_b32 v184, v170, v36
	ds_bpermute_b32 v185, v170, v37
	ds_bpermute_b32 v194, v170, v26
	ds_bpermute_b32 v195, v170, v27
	ds_bpermute_b32 v196, v170, v28
	ds_bpermute_b32 v197, v170, v29
	v_ashrrev_i32_e32 v139, 31, v138
	v_add_u32_e32 v198, 0xa0, v166
	v_lshlrev_b64 v[138:139], 6, v[138:139]
	v_and_b32_e32 v131, 0x7ff, v198
	v_cndmask_b32_e64 v131, v131, v165, s[6:7]
	v_lshl_add_u64 v[204:205], v[136:137], 0, v[138:139]
	v_lshlrev_b32_e32 v202, 7, v131
	v_mov_b32_e32 v203, v155
	v_lshl_add_u64 v[202:203], s[4:5], 0, v[202:203]
	v_lshl_add_u64 v[202:203], v[202:203], 0, v[154:155]
	v_ashrrev_i32_e32 v199, 31, v198
	v_lshlrev_b64 v[198:199], 7, v[198:199]
	v_lshl_add_u64 v[198:199], v[132:133], 0, v[198:199]
	s_waitcnt lgkmcnt(4)
; #define GAS __attribute__((address_space(1)))
; DI u32x4 pack8(const f32x4 a, const f32x4 b) { return (u32x4){pk2(a.x, a.y), pk2(a.z, a.w), pk2(b.x, b.y), pk2(b.z, b.w)}; }
;   DI void operator()(const acc_t& acc, const Unit& u, int, int, int, int) const {
;     ...
;       if (part == 1 && wc == 0) {
;         const GAS float* tab = (const GAS float*)(ws_ + OFF_ROPE);
;         GAS float* okr = out_ + (samp ? O_KRS : O_KRP);
;         GAS u16* kr = (GAS u16*)(ws_ + OFF_KROPE);
;         const int i0 = (8 * fq) & 15;
; #pragma unroll
;         for (int ai = 0; ai < 2; ++ai)
; #pragma unroll
;           for (int m = 0; m < 4; ++m) {
;             const int row = row0 + ai * 128 + m * 16, rl = rl0 + ai * 128 + m * 16;
;             const int ridx = samp ? 2048 + (rl & 63) : (rl & 2047);
;             f32x4 o[2];
; #pragma unroll
;             for (int n = 0; n < 2; ++n) {
;               const f32x4 cs = *(const GAS f32x4*)(tab + ridx * 32 + i0 + 4 * n), sn = *(const GAS f32x4*)(tab + ridx * 32 + 16 + i0 + 4 * n);
;               const f32x4 mine = acc[ai][1][m][n];
;               f32x4 oth; oth.x = __shfl_xor(mine.x, 32); oth.y = __shfl_xor(mine.y, 32); oth.z = __shfl_xor(mine.z, 32); oth.w = __shfl_xor(mine.w, 32);
;               o[n] = (fq < 2) ? (mine * cs - oth * sn) : (mine * cs + oth * sn);
;             }
;             *(GAS f32x4*)(okr + (size_t)rl * 32 + 8 * fq) = o[0]; *(GAS f32x4*)(okr + (size_t)rl * 32 + 8 * fq + 4) = o[1];
;             *(GAS u32x4*)(kr + (size_t)row * 32 + 8 * fq) = pack8(o[0], o[1]);
;           }
;       }
	v_pk_mul_f32 v[138:139], v[142:143], v[184:185]
	v_pk_mul_f32 v[140:141], v[140:141], v[168:169]
	s_waitcnt lgkmcnt(0)
	v_pk_mul_f32 v[142:143], v[174:175], v[196:197]
	v_pk_mul_f32 v[168:169], v[172:173], v[194:195]
	v_xor_b32_e32 v131, 0x80000000, v140
	v_xor_b32_e32 v135, 0x80000000, v141
	v_xor_b32_e32 v145, 0x80000000, v138
	v_xor_b32_e32 v165, 0x80000000, v139
	v_xor_b32_e32 v167, 0x80000000, v168
	v_xor_b32_e32 v171, 0x80000000, v169
	v_xor_b32_e32 v174, 0x80000000, v142
	v_xor_b32_e32 v175, 0x80000000, v143
	v_cndmask_b32_e32 v173, v139, v165, vcc
	v_cndmask_b32_e32 v172, v138, v145, vcc
	v_cndmask_b32_e32 v139, v141, v135, vcc
	v_cndmask_b32_e32 v138, v140, v131, vcc
	v_cndmask_b32_e32 v143, v143, v175, vcc
	v_cndmask_b32_e32 v142, v142, v174, vcc
	v_cndmask_b32_e32 v169, v169, v171, vcc
	v_cndmask_b32_e32 v168, v168, v167, vcc
	s_nop 0
	v_pk_fma_f32 v[138:139], v[34:35], v[176:177], v[138:139]
	v_pk_fma_f32 v[140:141], v[36:37], v[178:179], v[172:173]
	s_nop 0
	v_pk_fma_f32 v[172:173], v[26:27], v[180:181], v[168:169]
	v_pk_fma_f32 v[174:175], v[28:29], v[182:183], v[142:143]
	global_load_dwordx4 v[232:235], v[202:203], off offset:64
	global_load_dwordx4 v[236:239], v[202:203], off offset:80
	global_load_dwordx4 v[240:243], v[202:203], off
	global_load_dwordx4 v[244:247], v[202:203], off offset:16
	global_store_dwordx4 v[200:201], v[138:141], off
	global_store_dwordx4 v[200:201], v[172:175], off offset:16
	ds_bpermute_b32 v142, v170, v18
	v_cvt_pk_bf16_f32 v138, v138, v139
	v_cvt_pk_bf16_f32 v139, v140, v141
	v_cvt_pk_bf16_f32 v140, v172, v173
	v_cvt_pk_bf16_f32 v141, v174, v175
	global_store_dwordx4 v[204:205], v[138:141], off
	s_waitcnt vmcnt(3)
	v_mov_b32_e32 v138, v232
	v_mov_b32_e32 v139, v233
	v_mov_b32_e32 v140, v234
	v_mov_b32_e32 v141, v235
	v_mov_b32_e32 v172, v236
	v_mov_b32_e32 v173, v237
	v_mov_b32_e32 v174, v238
	v_mov_b32_e32 v175, v239
	v_mov_b32_e32 v176, v240
	v_mov_b32_e32 v177, v241
	v_mov_b32_e32 v178, v242
	v_mov_b32_e32 v179, v243
	v_mov_b32_e32 v180, v244
	v_mov_b32_e32 v181, v245
	v_mov_b32_e32 v182, v246
	v_mov_b32_e32 v183, v247
	ds_bpermute_b32 v143, v170, v19
	ds_bpermute_b32 v168, v170, v20
	ds_bpermute_b32 v169, v170, v21
	ds_bpermute_b32 v184, v170, v10
	ds_bpermute_b32 v185, v170, v11
	ds_bpermute_b32 v194, v170, v12
	ds_bpermute_b32 v195, v170, v13
	v_add_u32_e32 v196, 0xb0, v166
	v_and_b32_e32 v131, 0x7ff, v196
	v_cndmask_b32_e64 v131, v131, v144, s[6:7]
	v_mov_b32_e32 v145, v155
	v_lshlrev_b32_e32 v144, 7, v131
	v_lshl_add_u64 v[144:145], s[4:5], 0, v[144:145]
	v_lshl_add_u64 v[200:201], v[144:145], 0, v[154:155]
	v_ashrrev_i32_e32 v135, 31, v134
	v_lshlrev_b64 v[134:135], 6, v[134:135]
	v_lshl_add_u64 v[134:135], v[136:137], 0, v[134:135]
	v_ashrrev_i32_e32 v197, 31, v196
	s_waitcnt lgkmcnt(4)
	v_pk_mul_f32 v[140:141], v[140:141], v[168:169]
	v_pk_mul_f32 v[138:139], v[138:139], v[142:143]
	s_waitcnt lgkmcnt(0)
	v_pk_mul_f32 v[142:143], v[174:175], v[194:195]
	v_pk_mul_f32 v[144:145], v[172:173], v[184:185]
	v_xor_b32_e32 v131, 0x80000000, v138
	v_xor_b32_e32 v154, 0x80000000, v139
	v_xor_b32_e32 v165, 0x80000000, v140
	v_xor_b32_e32 v167, 0x80000000, v141
	v_xor_b32_e32 v171, 0x80000000, v144
	v_xor_b32_e32 v172, 0x80000000, v145
	v_xor_b32_e32 v168, 0x80000000, v142
	v_xor_b32_e32 v169, 0x80000000, v143
	v_cndmask_b32_e32 v141, v141, v167, vcc
	v_cndmask_b32_e32 v140, v140, v165, vcc
	v_cndmask_b32_e32 v139, v139, v154, vcc
	v_cndmask_b32_e32 v138, v138, v131, vcc
	v_cndmask_b32_e32 v169, v143, v169, vcc
	v_cndmask_b32_e32 v168, v142, v168, vcc
	v_cndmask_b32_e32 v143, v145, v172, vcc
	v_cndmask_b32_e32 v142, v144, v171, vcc
	s_nop 0
	v_pk_fma_f32 v[138:139], v[18:19], v[176:177], v[138:139]
	v_pk_fma_f32 v[140:141], v[20:21], v[178:179], v[140:141]
	s_nop 0
	v_pk_fma_f32 v[142:143], v[10:11], v[180:181], v[142:143]
	v_pk_fma_f32 v[144:145], v[12:13], v[182:183], v[168:169]
	global_load_dwordx4 v[232:235], v[200:201], off offset:64
	global_load_dwordx4 v[236:239], v[200:201], off offset:80
	global_load_dwordx4 v[240:243], v[200:201], off
	global_load_dwordx4 v[244:247], v[200:201], off offset:16
	global_store_dwordx4 v[198:199], v[138:141], off
	global_store_dwordx4 v[198:199], v[142:145], off offset:16
	ds_bpermute_b32 v168, v170, v8
	v_cvt_pk_bf16_f32 v138, v138, v139
	v_cvt_pk_bf16_f32 v139, v140, v141
	v_cvt_pk_bf16_f32 v140, v142, v143
	v_cvt_pk_bf16_f32 v141, v144, v145
	global_store_dwordx4 v[134:135], v[138:141], off
	s_waitcnt vmcnt(3)
	v_mov_b32_e32 v138, v232
	v_mov_b32_e32 v139, v233
	v_mov_b32_e32 v140, v234
	v_mov_b32_e32 v141, v235
	v_mov_b32_e32 v142, v236
	v_mov_b32_e32 v143, v237
	v_mov_b32_e32 v144, v238
	v_mov_b32_e32 v145, v239
	v_mov_b32_e32 v172, v240
	v_mov_b32_e32 v173, v241
	v_mov_b32_e32 v174, v242
	v_mov_b32_e32 v175, v243
	v_mov_b32_e32 v176, v244
	v_mov_b32_e32 v177, v245
	v_mov_b32_e32 v178, v246
	v_mov_b32_e32 v179, v247
	ds_bpermute_b32 v134, v170, v6
	ds_bpermute_b32 v135, v170, v7
	ds_bpermute_b32 v169, v170, v9
	ds_bpermute_b32 v180, v170, v2
	ds_bpermute_b32 v181, v170, v3
	ds_bpermute_b32 v182, v170, v4
	ds_bpermute_b32 v183, v170, v5
	v_ashrrev_i32_e32 v131, 31, v130
	v_lshlrev_b64 v[170:171], 6, v[130:131]
	v_lshlrev_b64 v[130:131], 7, v[196:197]
	v_lshl_add_u64 v[184:185], v[132:133], 0, v[130:131]
	s_waitcnt lgkmcnt(4)
	v_pk_mul_f32 v[130:131], v[140:141], v[168:169]
	v_pk_mul_f32 v[132:133], v[138:139], v[134:135]
	s_waitcnt lgkmcnt(0)
	v_pk_mul_f32 v[134:135], v[144:145], v[182:183]
	v_pk_mul_f32 v[138:139], v[142:143], v[180:181]
	v_xor_b32_e32 v142, 0x80000000, v132
	v_xor_b32_e32 v143, 0x80000000, v133
	v_xor_b32_e32 v140, 0x80000000, v130
	v_xor_b32_e32 v141, 0x80000000, v131
	v_xor_b32_e32 v144, 0x80000000, v138
	v_xor_b32_e32 v145, 0x80000000, v139
	v_xor_b32_e32 v154, 0x80000000, v134
	v_xor_b32_e32 v165, 0x80000000, v135
	v_cndmask_b32_e32 v141, v131, v141, vcc
	v_cndmask_b32_e32 v140, v130, v140, vcc
	v_cndmask_b32_e32 v131, v133, v143, vcc
	v_cndmask_b32_e32 v130, v132, v142, vcc
	v_cndmask_b32_e32 v135, v135, v165, vcc
	v_cndmask_b32_e32 v134, v134, v154, vcc
	v_cndmask_b32_e32 v139, v139, v145, vcc
	v_cndmask_b32_e32 v138, v138, v144, vcc
	s_nop 0
	v_pk_fma_f32 v[130:131], v[6:7], v[172:173], v[130:131]
	v_pk_fma_f32 v[132:133], v[8:9], v[174:175], v[140:141]
	s_nop 0
	v_pk_fma_f32 v[138:139], v[2:3], v[176:177], v[138:139]
	v_pk_fma_f32 v[140:141], v[4:5], v[178:179], v[134:135]
	global_store_dwordx4 v[184:185], v[130:133], off
	global_store_dwordx4 v[184:185], v[138:141], off offset:16
	v_lshl_add_u64 v[134:135], v[136:137], 0, v[170:171]
	v_cvt_pk_bf16_f32 v130, v130, v131
	v_cvt_pk_bf16_f32 v131, v132, v133
	v_cvt_pk_bf16_f32 v132, v138, v139
	v_cvt_pk_bf16_f32 v133, v140, v141
	global_store_dwordx4 v[134:135], v[130:133], off

; #define PG8_STAGE(bufoff, gbase, voff) do { _Pragma("unroll") for (int _i = 0; _i < 2; ++_i) \
;     __builtin_amdgcn_global_load_lds((const unsigned*)((const char*)(gbase) + (voff)[_i]), (LAS unsigned*)(lds + (bufoff) + ldsw + _i * 8192), 16, 0, 0); } while (0)
; #define PG8_LDA(dst, b, h) do { _Pragma("unroll") for (int m = 0; m < 4; ++m) _Pragma("unroll") for (int k = 0; k < 2; ++k) dst[m][k] = *(const LAS bf16x8*)(lds + PG8_SA(b, h) + aoff + m * 2048 + k * 1024); } while (0)
; #define PG8_LDB(dst, b, h) do { _Pragma("unroll") for (int n = 0; n < 2; ++n) _Pragma("unroll") for (int k = 0; k < 2; ++k) dst[n][k] = *(const LAS bf16x8*)(lds + PG8_SB(b, h) + boff + n * 2048 + k * 1024); } while (0)
; #define PG8_MMA(ai, bj, At, Bt) do { __builtin_amdgcn_s_setprio(1); _Pragma("unroll") for (int m = 0; m < 4; ++m) _Pragma("unroll") for (int n = 0; n < 2; ++n) _Pragma("unroll") for (int k = 0; k < 2; ++k) \
;     acc[ai][bj][m][n] = __builtin_amdgcn_mfma_f32_16x16x32_bf16(Bt[n][k], At[m][k], acc[ai][bj][m][n], 0, 0, 0); __builtin_amdgcn_s_setprio(0); } while (0)
; #define PG8_WAIT_V(n) asm volatile("s_waitcnt vmcnt(" #n ")" ::: "memory")
; #define PG8_WAIT_L(n) asm volatile("s_waitcnt lgkmcnt(" #n ")" ::: "memory")
; #define PG8_BAR __builtin_amdgcn_s_barrier()
; #define PG8_SCHED __builtin_amdgcn_sched_barrier(0)
; template <class Epi>
; DI void gemm_phase(LAS unsigned char* lds, const u16* Ag, const u16* Btg, const int K, const StaticOrder& S, const Epi& E) {
;     ...
;       PG8_LDB(B0, 0, 0); PG8_SCHED; PG8_LDA(At, 0, 0); PG8_STAGE(PG8_SA(1, 1), a1 + hstep, voffA);
;       PG8_WAIT_L(8); PG8_BAR; PG8_WAIT_L(0); PG8_MMA(0, 0, At, B0); PG8_BAR; PG8_SCHED;
;       PG8_LDB(B1, 0, 1); PG8_STAGE(PG8_SB(0, 0), b2, voffB);
;       PG8_BAR; PG8_WAIT_L(0); PG8_MMA(0, 1, At, B1); PG8_BAR;
;       PG8_LDA(At, 0, 1); PG8_STAGE(PG8_SA(0, 0), a2, voffA);
;       PG8_BAR; PG8_WAIT_L(0); PG8_MMA(1, 0, At, B0); PG8_BAR; PG8_SCHED;
;       PG8_STAGE(PG8_SB(0, 1), b2 + hstep, voffB);
;       PG8_WAIT_V(6); PG8_BAR; PG8_MMA(1, 1, At, B1); PG8_BAR;
.LBB0_295:
	ds_read_b128 v[144:147], v161
	ds_read_b128 v[148:151], v161 offset:1024
	ds_read_b128 v[152:155], v161 offset:2048
	ds_read_b128 v[156:159], v161 offset:3072
	s_add_u32 s4, s8, 0x100
	s_addc_u32 s5, s9, 0
	s_cmp_eq_u32 s38, 2
	s_cselect_b32 s11, s25, s5
	s_cselect_b32 s10, s24, s4
	s_cselect_b32 s7, s27, s37
	s_cselect_b32 s6, s26, s35
	v_lshl_add_u64 v[200:201], s[8:9], 0, v[136:137]
	s_add_i32 m0, s49, 0xc000
	ds_read_b128 v[166:169], v162
	ds_read_b128 v[170:173], v162 offset:1024
	ds_read_b128 v[174:177], v162 offset:2048
	ds_read_b128 v[178:181], v162 offset:3072
	ds_read_b128 v[182:185], v162 offset:4096
	ds_read_b128 v[188:191], v162 offset:5120
	ds_read_b128 v[192:195], v162 offset:6144
	ds_read_b128 v[196:199], v162 offset:7168
	global_load_lds_dwordx4 v[200:201], off
	v_lshl_add_u64 v[200:201], s[8:9], 0, v[138:139]
	s_add_i32 m0, s49, 0xe000
	s_nop 0
	global_load_lds_dwordx4 v[200:201], off
	s_waitcnt lgkmcnt(8)
	s_barrier
	s_waitcnt lgkmcnt(0)
	s_setprio 1
	s_waitcnt lgkmcnt(0)
	v_mfma_f32_16x16x32_bf16 v[126:129], v[144:147], v[166:169], v[126:129]
	v_mfma_f32_16x16x32_bf16 v[122:125], v[152:155], v[166:169], v[122:125]
	v_mfma_f32_16x16x32_bf16 v[110:113], v[144:147], v[174:177], v[110:113]
	v_mfma_f32_16x16x32_bf16 v[106:109], v[152:155], v[174:177], v[106:109]
	v_mfma_f32_16x16x32_bf16 v[94:97], v[144:147], v[182:185], v[94:97]
	v_mfma_f32_16x16x32_bf16 v[90:93], v[152:155], v[182:185], v[90:93]
	v_mfma_f32_16x16x32_bf16 v[78:81], v[144:147], v[192:195], v[78:81]
	v_mfma_f32_16x16x32_bf16 v[74:77], v[152:155], v[192:195], v[74:77]
	v_mfma_f32_16x16x32_bf16 v[126:129], v[148:151], v[170:173], v[126:129]
	v_mfma_f32_16x16x32_bf16 v[122:125], v[156:159], v[170:173], v[122:125]
	v_mfma_f32_16x16x32_bf16 v[110:113], v[148:151], v[178:181], v[110:113]
	v_mfma_f32_16x16x32_bf16 v[106:109], v[156:159], v[178:181], v[106:109]
	v_mfma_f32_16x16x32_bf16 v[94:97], v[148:151], v[188:191], v[94:97]
	v_mfma_f32_16x16x32_bf16 v[90:93], v[156:159], v[188:191], v[90:93]
	v_mfma_f32_16x16x32_bf16 v[78:81], v[148:151], v[196:199], v[78:81]
	v_mfma_f32_16x16x32_bf16 v[74:77], v[156:159], v[196:199], v[74:77]
	s_setprio 0
	s_barrier
	s_add_i32 s8, s64, s48
	v_lshl_add_u64 v[216:217], s[6:7], 0, v[130:131]
	s_mov_b32 m0, s8
	ds_read_b128 v[200:203], v163
	ds_read_b128 v[204:207], v163 offset:1024
	ds_read_b128 v[208:211], v163 offset:2048
	ds_read_b128 v[212:215], v163 offset:3072
	global_load_lds_dwordx4 v[216:217], off
	v_lshl_add_u64 v[218:219], s[6:7], 0, v[132:133]
	s_add_i32 m0, s8, 0x2000
	s_nop 0
	global_load_lds_dwordx4 v[218:219], off
	s_barrier
	s_waitcnt lgkmcnt(0)
	s_setprio 1
	s_waitcnt lgkmcnt(0)
	v_mfma_f32_16x16x32_bf16 v[118:121], v[200:203], v[166:169], v[118:121]
	v_mfma_f32_16x16x32_bf16 v[114:117], v[208:211], v[166:169], v[114:117]
	v_mfma_f32_16x16x32_bf16 v[102:105], v[200:203], v[174:177], v[102:105]
	v_mfma_f32_16x16x32_bf16 v[98:101], v[208:211], v[174:177], v[98:101]
	v_mfma_f32_16x16x32_bf16 v[86:89], v[200:203], v[182:185], v[86:89]
	v_mfma_f32_16x16x32_bf16 v[82:85], v[208:211], v[182:185], v[82:85]
	v_mfma_f32_16x16x32_bf16 v[70:73], v[200:203], v[192:195], v[70:73]
	v_mfma_f32_16x16x32_bf16 v[66:69], v[208:211], v[192:195], v[66:69]
	v_mfma_f32_16x16x32_bf16 v[118:121], v[204:207], v[170:173], v[118:121]
	v_mfma_f32_16x16x32_bf16 v[114:117], v[212:215], v[170:173], v[114:117]
	v_mfma_f32_16x16x32_bf16 v[102:105], v[204:207], v[178:181], v[102:105]
	v_mfma_f32_16x16x32_bf16 v[98:101], v[212:215], v[178:181], v[98:101]
	v_mfma_f32_16x16x32_bf16 v[86:89], v[204:207], v[188:191], v[86:89]
	v_mfma_f32_16x16x32_bf16 v[82:85], v[212:215], v[188:191], v[82:85]
	v_mfma_f32_16x16x32_bf16 v[70:73], v[204:207], v[196:199], v[70:73]
	v_mfma_f32_16x16x32_bf16 v[66:69], v[212:215], v[196:199], v[66:69]
	s_setprio 0
	s_mov_b32 m0, s49
	v_lshl_add_u64 v[220:221], s[10:11], 0, v[130:131]
	s_barrier
	ds_read_b128 v[166:169], v162 offset:16384
	ds_read_b128 v[170:173], v162 offset:17408
	ds_read_b128 v[174:177], v162 offset:18432
	ds_read_b128 v[178:181], v162 offset:19456
	ds_read_b128 v[182:185], v162 offset:20480
	ds_read_b128 v[188:191], v162 offset:21504
	ds_read_b128 v[192:195], v162 offset:22528
	ds_read_b128 v[196:199], v162 offset:23552
	global_load_lds_dwordx4 v[220:221], off
	v_lshl_add_u64 v[222:223], s[10:11], 0, v[132:133]
	s_mov_b32 m0, s50
	s_nop 0
	global_load_lds_dwordx4 v[222:223], off
	s_barrier
	s_waitcnt lgkmcnt(0)
	s_setprio 1
	s_waitcnt lgkmcnt(0)
	v_mfma_f32_16x16x32_bf16 v[62:65], v[144:147], v[166:169], v[62:65]
	v_mfma_f32_16x16x32_bf16 v[58:61], v[152:155], v[166:169], v[58:61]
	v_mfma_f32_16x16x32_bf16 v[46:49], v[144:147], v[174:177], v[46:49]
	v_mfma_f32_16x16x32_bf16 v[42:45], v[152:155], v[174:177], v[42:45]
	v_mfma_f32_16x16x32_bf16 v[30:33], v[144:147], v[182:185], v[30:33]
	v_mfma_f32_16x16x32_bf16 v[26:29], v[152:155], v[182:185], v[26:29]
	v_mfma_f32_16x16x32_bf16 v[14:17], v[144:147], v[192:195], v[14:17]
	v_mfma_f32_16x16x32_bf16 v[10:13], v[152:155], v[192:195], v[10:13]
	v_mfma_f32_16x16x32_bf16 v[62:65], v[148:151], v[170:173], v[62:65]
	v_mfma_f32_16x16x32_bf16 v[58:61], v[156:159], v[170:173], v[58:61]
	v_mfma_f32_16x16x32_bf16 v[46:49], v[148:151], v[178:181], v[46:49]
	v_mfma_f32_16x16x32_bf16 v[42:45], v[156:159], v[178:181], v[42:45]
	v_mfma_f32_16x16x32_bf16 v[30:33], v[148:151], v[188:191], v[30:33]
	v_mfma_f32_16x16x32_bf16 v[26:29], v[156:159], v[188:191], v[26:29]
	v_mfma_f32_16x16x32_bf16 v[14:17], v[148:151], v[196:199], v[14:17]
	v_mfma_f32_16x16x32_bf16 v[10:13], v[156:159], v[196:199], v[10:13]
	s_setprio 0
	s_barrier
; #define PG8_STAGE(bufoff, gbase, voff) do { _Pragma("unroll") for (int _i = 0; _i < 2; ++_i) \
;     __builtin_amdgcn_global_load_lds((const unsigned*)((const char*)(gbase) + (voff)[_i]), (LAS unsigned*)(lds + (bufoff) + ldsw + _i * 8192), 16, 0, 0); } while (0)
; #define PG8_LDA(dst, b, h) do { _Pragma("unroll") for (int m = 0; m < 4; ++m) _Pragma("unroll") for (int k = 0; k < 2; ++k) dst[m][k] = *(const LAS bf16x8*)(lds + PG8_SA(b, h) + aoff + m * 2048 + k * 1024); } while (0)
; #define PG8_LDB(dst, b, h) do { _Pragma("unroll") for (int n = 0; n < 2; ++n) _Pragma("unroll") for (int k = 0; k < 2; ++k) dst[n][k] = *(const LAS bf16x8*)(lds + PG8_SB(b, h) + boff + n * 2048 + k * 1024); } while (0)
; #define PG8_MMA(ai, bj, At, Bt) do { __builtin_amdgcn_s_setprio(1); _Pragma("unroll") for (int m = 0; m < 4; ++m) _Pragma("unroll") for (int n = 0; n < 2; ++n) _Pragma("unroll") for (int k = 0; k < 2; ++k) \
;     acc[ai][bj][m][n] = __builtin_amdgcn_mfma_f32_16x16x32_bf16(Bt[n][k], At[m][k], acc[ai][bj][m][n], 0, 0, 0); __builtin_amdgcn_s_setprio(0); } while (0)
; #define PG8_WAIT_V(n) asm volatile("s_waitcnt vmcnt(" #n ")" ::: "memory")
; #define PG8_WAIT_L(n) asm volatile("s_waitcnt lgkmcnt(" #n ")" ::: "memory")
; #define PG8_BAR __builtin_amdgcn_s_barrier()
; #define PG8_SCHED __builtin_amdgcn_sched_barrier(0)
; template <class Epi>
; DI void gemm_phase(LAS unsigned char* lds, const u16* Ag, const u16* Btg, const int K, const StaticOrder& S, const Epi& E) {
;     ...
;       PG8_WAIT_V(6); PG8_BAR; PG8_MMA(1, 1, At, B1); PG8_BAR;
;       PG8_LDB(B0, 1, 0); PG8_SCHED; PG8_LDA(At, 1, 0); PG8_STAGE(PG8_SA(0, 1), a2 + hstep, voffA);
;       PG8_WAIT_L(8); PG8_BAR; PG8_WAIT_L(0); PG8_MMA(0, 0, At, B0); PG8_BAR; PG8_SCHED;
;       PG8_LDB(B1, 1, 1); PG8_STAGE(PG8_SB(1, 0), b3, voffB);
;       PG8_BAR; PG8_WAIT_L(0); PG8_MMA(0, 1, At, B1); PG8_BAR;
;       PG8_LDA(At, 1, 1); PG8_STAGE(PG8_SA(1, 0), a3, voffA);
;       PG8_BAR; PG8_WAIT_L(0); PG8_MMA(1, 0, At, B0); PG8_BAR; PG8_SCHED;
	s_add_u32 s8, s6, 0x18000
	s_addc_u32 s9, s7, 0
	s_add_i32 s39, s65, s48
	v_lshl_add_u64 v[144:145], s[8:9], 0, v[130:131]
	s_mov_b32 m0, s39
	s_nop 0
	global_load_lds_dwordx4 v[144:145], off
	v_lshl_add_u64 v[144:145], s[8:9], 0, v[132:133]
	s_add_i32 m0, s39, 0x2000
	s_nop 0
	global_load_lds_dwordx4 v[144:145], off
	s_waitcnt vmcnt(6)
	s_barrier
	s_setprio 1
	v_mfma_f32_16x16x32_bf16 v[54:57], v[200:203], v[166:169], v[54:57]
	v_mfma_f32_16x16x32_bf16 v[50:53], v[208:211], v[166:169], v[50:53]
	v_mfma_f32_16x16x32_bf16 v[38:41], v[200:203], v[174:177], v[38:41]
	v_mfma_f32_16x16x32_bf16 v[34:37], v[208:211], v[174:177], v[34:37]
	v_mfma_f32_16x16x32_bf16 v[22:25], v[200:203], v[182:185], v[22:25]
	v_mfma_f32_16x16x32_bf16 v[18:21], v[208:211], v[182:185], v[18:21]
	v_mfma_f32_16x16x32_bf16 v[6:9], v[200:203], v[192:195], v[6:9]
	v_mfma_f32_16x16x32_bf16 v[2:5], v[208:211], v[192:195], v[2:5]
	v_mfma_f32_16x16x32_bf16 v[54:57], v[204:207], v[170:173], v[54:57]
	v_mfma_f32_16x16x32_bf16 v[50:53], v[212:215], v[170:173], v[50:53]
	v_mfma_f32_16x16x32_bf16 v[38:41], v[204:207], v[178:181], v[38:41]
	v_mfma_f32_16x16x32_bf16 v[34:37], v[212:215], v[178:181], v[34:37]
	v_mfma_f32_16x16x32_bf16 v[22:25], v[204:207], v[188:191], v[22:25]
	v_mfma_f32_16x16x32_bf16 v[18:21], v[212:215], v[188:191], v[18:21]
	v_mfma_f32_16x16x32_bf16 v[6:9], v[204:207], v[196:199], v[6:9]
	v_mfma_f32_16x16x32_bf16 v[2:5], v[212:215], v[196:199], v[2:5]
	s_setprio 0
	s_add_i32 s39, 16, 0x18000
	v_add_u32_e32 v134, s39, v160
	s_barrier
	ds_read_b128 v[144:147], v134
	ds_read_b128 v[148:151], v134 offset:1024
	ds_read_b128 v[152:155], v134 offset:2048
	ds_read_b128 v[156:159], v134 offset:3072
	s_add_u32 s8, s10, 0x18000
	s_addc_u32 s9, s11, 0
	s_mov_b32 m0, s51
	v_lshl_add_u64 v[200:201], s[8:9], 0, v[130:131]
	ds_read_b128 v[166:169], v162 offset:32768
	ds_read_b128 v[170:173], v162 offset:33792
	ds_read_b128 v[174:177], v162 offset:34816
	ds_read_b128 v[178:181], v162 offset:35840
	ds_read_b128 v[182:185], v162 offset:36864
	ds_read_b128 v[188:191], v162 offset:37888
	ds_read_b128 v[192:195], v162 offset:38912
	ds_read_b128 v[196:199], v162 offset:39936
	global_load_lds_dwordx4 v[200:201], off
	v_lshl_add_u64 v[200:201], s[8:9], 0, v[132:133]
	s_mov_b32 m0, s52
	s_nop 0
	global_load_lds_dwordx4 v[200:201], off
	s_waitcnt lgkmcnt(8)
	s_barrier
	s_waitcnt lgkmcnt(0)
	s_setprio 1
	s_waitcnt lgkmcnt(0)
	v_mfma_f32_16x16x32_bf16 v[126:129], v[144:147], v[166:169], v[126:129]
	v_mfma_f32_16x16x32_bf16 v[122:125], v[152:155], v[166:169], v[122:125]
	v_mfma_f32_16x16x32_bf16 v[110:113], v[144:147], v[174:177], v[110:113]
	v_mfma_f32_16x16x32_bf16 v[106:109], v[152:155], v[174:177], v[106:109]
	v_mfma_f32_16x16x32_bf16 v[94:97], v[144:147], v[182:185], v[94:97]
	v_mfma_f32_16x16x32_bf16 v[90:93], v[152:155], v[182:185], v[90:93]
	v_mfma_f32_16x16x32_bf16 v[78:81], v[144:147], v[192:195], v[78:81]
	v_mfma_f32_16x16x32_bf16 v[74:77], v[152:155], v[192:195], v[74:77]
	v_mfma_f32_16x16x32_bf16 v[126:129], v[148:151], v[170:173], v[126:129]
	v_mfma_f32_16x16x32_bf16 v[122:125], v[156:159], v[170:173], v[122:125]
	v_mfma_f32_16x16x32_bf16 v[110:113], v[148:151], v[178:181], v[110:113]
	v_mfma_f32_16x16x32_bf16 v[106:109], v[156:159], v[178:181], v[106:109]
	v_mfma_f32_16x16x32_bf16 v[94:97], v[148:151], v[188:191], v[94:97]
	v_mfma_f32_16x16x32_bf16 v[90:93], v[156:159], v[188:191], v[90:93]
	v_mfma_f32_16x16x32_bf16 v[78:81], v[148:151], v[196:199], v[78:81]
	v_mfma_f32_16x16x32_bf16 v[74:77], v[156:159], v[196:199], v[74:77]
	s_setprio 0
	s_barrier
	s_add_i32 s8, 16, 0x1c000
	s_add_i32 s9, s39, s48
	v_add_u32_e32 v134, s8, v160
	v_lshl_add_u64 v[216:217], v[216:217], 0, s[20:21]
	s_mov_b32 m0, s9
	ds_read_b128 v[200:203], v134
	ds_read_b128 v[204:207], v134 offset:1024
	ds_read_b128 v[208:211], v134 offset:2048
	ds_read_b128 v[212:215], v134 offset:3072
	global_load_lds_dwordx4 v[216:217], off
	v_lshl_add_u64 v[216:217], v[218:219], 0, s[20:21]
	s_add_i32 m0, s9, 0x2000
	s_nop 0
	global_load_lds_dwordx4 v[216:217], off
	s_barrier
	s_waitcnt lgkmcnt(0)
	s_setprio 1
	s_waitcnt lgkmcnt(0)
	v_mfma_f32_16x16x32_bf16 v[118:121], v[200:203], v[166:169], v[118:121]
	v_mfma_f32_16x16x32_bf16 v[114:117], v[208:211], v[166:169], v[114:117]
	v_mfma_f32_16x16x32_bf16 v[102:105], v[200:203], v[174:177], v[102:105]
	v_mfma_f32_16x16x32_bf16 v[98:101], v[208:211], v[174:177], v[98:101]
	v_mfma_f32_16x16x32_bf16 v[86:89], v[200:203], v[182:185], v[86:89]
	v_mfma_f32_16x16x32_bf16 v[82:85], v[208:211], v[182:185], v[82:85]
	v_mfma_f32_16x16x32_bf16 v[70:73], v[200:203], v[192:195], v[70:73]
	v_mfma_f32_16x16x32_bf16 v[66:69], v[208:211], v[192:195], v[66:69]
	v_mfma_f32_16x16x32_bf16 v[118:121], v[204:207], v[170:173], v[118:121]
	v_mfma_f32_16x16x32_bf16 v[114:117], v[212:215], v[170:173], v[114:117]
	v_mfma_f32_16x16x32_bf16 v[102:105], v[204:207], v[178:181], v[102:105]
	v_mfma_f32_16x16x32_bf16 v[98:101], v[212:215], v[178:181], v[98:101]
	v_mfma_f32_16x16x32_bf16 v[86:89], v[204:207], v[188:191], v[86:89]
	v_mfma_f32_16x16x32_bf16 v[82:85], v[212:215], v[188:191], v[82:85]
	v_mfma_f32_16x16x32_bf16 v[70:73], v[204:207], v[196:199], v[70:73]
	v_mfma_f32_16x16x32_bf16 v[66:69], v[212:215], v[196:199], v[66:69]
	s_setprio 0
	s_mov_b32 m0, s53
	v_lshl_add_u64 v[216:217], v[220:221], 0, s[20:21]
	s_barrier
	ds_read_b128 v[166:169], v162 offset:49152
	ds_read_b128 v[170:173], v162 offset:50176
	ds_read_b128 v[174:177], v162 offset:51200
	ds_read_b128 v[178:181], v162 offset:52224
	ds_read_b128 v[182:185], v162 offset:53248
	ds_read_b128 v[188:191], v162 offset:54272
	ds_read_b128 v[192:195], v162 offset:55296
	ds_read_b128 v[196:199], v162 offset:56320
	global_load_lds_dwordx4 v[216:217], off
	v_lshl_add_u64 v[216:217], v[222:223], 0, s[20:21]
	s_mov_b32 m0, s60
	s_nop 0
	global_load_lds_dwordx4 v[216:217], off
	s_barrier
; #define GAS __attribute__((address_space(1)))
; #define PG8_STAGE(bufoff, gbase, voff) do { _Pragma("unroll") for (int _i = 0; _i < 2; ++_i) \
;     __builtin_amdgcn_global_load_lds((const unsigned*)((const char*)(gbase) + (voff)[_i]), (LAS unsigned*)(lds + (bufoff) + ldsw + _i * 8192), 16, 0, 0); } while (0)
; #define PG8_MMA(ai, bj, At, Bt) do { __builtin_amdgcn_s_setprio(1); _Pragma("unroll") for (int m = 0; m < 4; ++m) _Pragma("unroll") for (int n = 0; n < 2; ++n) _Pragma("unroll") for (int k = 0; k < 2; ++k) \
;     acc[ai][bj][m][n] = __builtin_amdgcn_mfma_f32_16x16x32_bf16(Bt[n][k], At[m][k], acc[ai][bj][m][n], 0, 0, 0); __builtin_amdgcn_s_setprio(0); } while (0)
; #define PG8_WAIT_V(n) asm volatile("s_waitcnt vmcnt(" #n ")" ::: "memory")
; #define PG8_WAIT_L(n) asm volatile("s_waitcnt lgkmcnt(" #n ")" ::: "memory")
; #define PG8_BAR __builtin_amdgcn_s_barrier()
; template <class Epi>
; DI void gemm_phase(LAS unsigned char* lds, const u16* Ag, const u16* Btg, const int K, const StaticOrder& S, const Epi& E) {
;     ...
;       PG8_BAR; PG8_WAIT_L(0); PG8_MMA(1, 0, At, B0); PG8_BAR; PG8_SCHED;
;       PG8_STAGE(PG8_SB(1, 1), b3 + hstep, voffB);
;       PG8_WAIT_V(6); PG8_BAR; PG8_MMA(1, 1, At, B1); PG8_BAR;
;   DI void operator()(const acc_t& acc, const Unit& u, int, int, int, int) const {
;     ...
;     const bool samp = u.pm >= 256;
;     const int row0 = u.pm * 256 + wr * 64 + fr;
;     const GAS float* cqss = (const GAS float*)(ws_ + OFF_CQSS);
;     const GAS float* tab = (const GAS float*)(ws_ + OFF_ROPE);
;     GAS u16* dst = (GAS u16*)(ws_ + OFF_QMLA);
; #pragma unroll
;     for (int ai = 0; ai < 2; ++ai)
; #pragma unroll
;       for (int m = 0; m < 4; ++m) {
;         const int row = row0 + ai * 128 + m * 16;
;         const float r = rsqrtf((cqss[row] + cqss[NTOK + row]) * (1.f / 384.f) + EPS) * QS_MLA;
;         const int ridx = samp ? 2048 + ((row - NTOK_P) & 63) : (row & 2047);
; #pragma unroll
;         for (int bj = 0; bj < 2; ++bj) {
;           const int gi = u.pn * 8 + bj * 4 + wc;
;           f32x4 x1 = acc[ai][bj][m][0] * r, x2 = acc[ai][bj][m][1] * r;
;           if (gi % 3 == 2) {
;             const f32x4 cs = *(const GAS f32x4*)(tab + ridx * 32 + 4 * fq), sn = *(const GAS f32x4*)(tab + ridx * 32 + 16 + 4 * fq);
;             const f32x4 o1 = x1 * cs - x2 * sn, o2 = x2 * cs + x1 * sn;
;             x1 = o1; x2 = o2;
;           }
	s_waitcnt lgkmcnt(0)
	s_setprio 1
	s_waitcnt lgkmcnt(0)
	v_mfma_f32_16x16x32_bf16 v[62:65], v[144:147], v[166:169], v[62:65]
	v_mfma_f32_16x16x32_bf16 v[58:61], v[152:155], v[166:169], v[58:61]
	v_mfma_f32_16x16x32_bf16 v[46:49], v[144:147], v[174:177], v[46:49]
	v_mfma_f32_16x16x32_bf16 v[42:45], v[152:155], v[174:177], v[42:45]
	v_mfma_f32_16x16x32_bf16 v[30:33], v[144:147], v[182:185], v[30:33]
	v_mfma_f32_16x16x32_bf16 v[26:29], v[152:155], v[182:185], v[26:29]
	v_mfma_f32_16x16x32_bf16 v[14:17], v[144:147], v[192:195], v[14:17]
	v_mfma_f32_16x16x32_bf16 v[10:13], v[152:155], v[192:195], v[10:13]
	v_mfma_f32_16x16x32_bf16 v[62:65], v[148:151], v[170:173], v[62:65]
	v_mfma_f32_16x16x32_bf16 v[58:61], v[156:159], v[170:173], v[58:61]
	v_mfma_f32_16x16x32_bf16 v[46:49], v[148:151], v[178:181], v[46:49]
	v_mfma_f32_16x16x32_bf16 v[42:45], v[156:159], v[178:181], v[42:45]
	v_mfma_f32_16x16x32_bf16 v[30:33], v[148:151], v[188:191], v[30:33]
	v_mfma_f32_16x16x32_bf16 v[26:29], v[156:159], v[188:191], v[26:29]
	v_mfma_f32_16x16x32_bf16 v[14:17], v[148:151], v[196:199], v[14:17]
	v_mfma_f32_16x16x32_bf16 v[10:13], v[156:159], v[196:199], v[10:13]
	s_setprio 0
	s_barrier
	s_add_u32 s6, s6, 0x18080
	s_addc_u32 s7, s7, 0
	s_add_i32 s8, s8, s48
	v_lshl_add_u64 v[144:145], s[6:7], 0, v[130:131]
	s_mov_b32 m0, s8
	s_nop 0
	global_load_lds_dwordx4 v[144:145], off
	v_lshl_add_u64 v[144:145], s[6:7], 0, v[132:133]
	s_add_i32 m0, s8, 0x2000
	s_nop 0
	global_load_lds_dwordx4 v[144:145], off
	s_waitcnt vmcnt(6)
	s_barrier
	s_setprio 1
	v_mfma_f32_16x16x32_bf16 v[54:57], v[200:203], v[166:169], v[54:57]
	v_mfma_f32_16x16x32_bf16 v[50:53], v[208:211], v[166:169], v[50:53]
	v_mfma_f32_16x16x32_bf16 v[38:41], v[200:203], v[174:177], v[38:41]
	v_mfma_f32_16x16x32_bf16 v[34:37], v[208:211], v[174:177], v[34:37]
	v_mfma_f32_16x16x32_bf16 v[22:25], v[200:203], v[182:185], v[22:25]
	v_mfma_f32_16x16x32_bf16 v[18:21], v[208:211], v[182:185], v[18:21]
	v_mfma_f32_16x16x32_bf16 v[6:9], v[200:203], v[192:195], v[6:9]
	v_mfma_f32_16x16x32_bf16 v[2:5], v[208:211], v[192:195], v[2:5]
	v_mfma_f32_16x16x32_bf16 v[54:57], v[204:207], v[170:173], v[54:57]
	v_mfma_f32_16x16x32_bf16 v[50:53], v[212:215], v[170:173], v[50:53]
	v_mfma_f32_16x16x32_bf16 v[38:41], v[204:207], v[178:181], v[38:41]
	v_mfma_f32_16x16x32_bf16 v[34:37], v[212:215], v[178:181], v[34:37]
	v_mfma_f32_16x16x32_bf16 v[22:25], v[204:207], v[188:191], v[22:25]
	v_mfma_f32_16x16x32_bf16 v[18:21], v[212:215], v[188:191], v[18:21]
	v_mfma_f32_16x16x32_bf16 v[6:9], v[204:207], v[196:199], v[6:9]
	v_mfma_f32_16x16x32_bf16 v[2:5], v[212:215], v[196:199], v[2:5]
	s_setprio 0
	s_add_i32 s38, s38, 2
	s_add_u32 s35, s35, 0x100
	s_addc_u32 s37, s37, 0
	s_cmp_gt_u32 s38, 3
	s_mov_b64 s[8:9], s[4:5]
	s_barrier
	s_cbranch_scc0 .LBB0_295
	v_mov_b32_e32 v134, v1
	s_mov_b64 s[4:5], s[58:59]
	v_readfirstlane_b32 s10, v134
	s_bfe_u32 s11, s10, 0x20006
	s_mov_b64 s[6:7], s[56:57]
	s_cmpk_gt_i32 s34, 0xff
	v_and_b32_e32 v166, 15, v134
	s_cselect_b64 s[8:9], -1, 0
	s_mov_b32 s98, 0x2800
	s_cselect_b32 s98, 0xffffe800, s98
	s_cselect_b32 s99, -1, 0
	s_mov_b64 s[96:97], 0x800
	s_ashr_i32 s6, s10, 2
	s_andn2_b32 s6, s6, 63
	v_lshl_or_b32 v144, s34, 8, v166
	s_add_u32 s40, s4, 0xa62100
	v_add_u32_e32 v146, s6, v144
	s_addc_u32 s41, s5, 0
	v_ashrrev_i32_e32 v147, 31, v146
	v_lshl_add_u64 v[150:151], v[146:147], 2, s[40:41]
	v_add_co_u32_e32 v148, vcc, s66, v150
	v_lshrrev_b32_e32 v134, 2, v134
	s_nop 0
	v_addc_co_u32_e32 v149, vcc, 0, v151, vcc
	global_load_dword v154, v[150:151], off
	global_load_dword v155, v[148:149], off
	global_load_dword v232, v[150:151], off offset:64
	global_load_dword v233, v[148:149], off offset:64
	global_load_dword v234, v[150:151], off offset:128
	global_load_dword v235, v[148:149], off offset:128
	global_load_dword v236, v[150:151], off offset:192
	global_load_dword v237, v[148:149], off offset:192
	global_load_dword v238, v[150:151], off offset:512
	global_load_dword v239, v[148:149], off offset:512
	global_load_dword v240, v[150:151], off offset:576
	global_load_dword v241, v[148:149], off offset:576
	global_load_dword v242, v[150:151], off offset:640
	global_load_dword v243, v[148:149], off offset:640
	global_load_dword v244, v[150:151], off offset:704
	global_load_dword v245, v[148:149], off offset:704
	v_or_b32_e32 v165, 0x800, v166
	v_and_b32_e32 v147, 12, v134
	v_and_b32_e32 v134, 0x7cf, v146
	s_add_u32 s34, s4, 0x90100
	v_cndmask_b32_e64 v134, v134, v165, s[8:9]
	s_addc_u32 s35, s5, 0
	v_lshlrev_b32_e32 v134, 7, v134
	v_lshl_add_u64 v[152:153], s[34:35], 0, v[134:135]
	v_mov_b32_e32 v145, v135
	v_lshlrev_b32_e32 v144, 2, v147
	v_lshl_add_u64 v[152:153], v[152:153], 0, v[144:145]
	v_mov_b32_e32 v246, v152
	v_mov_b32_e32 v247, v153
	global_load_dwordx4 v[248:251], v[246:247], off offset:64
	global_load_dwordx4 v[252:255], v[246:247], off
	s_lshl_b32 s6, s36, 3
	s_or_b32 s6, s11, s6
	s_mul_hi_i32 s7, s6, 0x55555556
	s_lshr_b32 s10, s7, 31
	s_add_i32 s7, s7, s10
	s_mul_i32 s7, s7, 3
	s_sub_i32 s7, s6, s7
	s_cmp_eq_u32 s7, 2
	s_cselect_b64 s[10:11], -1, 0
	s_cmp_lg_u32 s7, 2
	s_waitcnt vmcnt(0)
	v_add_f32_e32 v134, v154, v155
	v_fmamk_f32 v134, v134, 0x3b2aaaab, v164
	v_mul_f32_e32 v145, 0x4b800000, v134
	v_cmp_gt_f32_e32 vcc, s67, v134
	s_nop 1
	v_cndmask_b32_e32 v134, v134, v145, vcc
	v_rsq_f32_e32 v134, v134
	s_nop 0
	v_mul_f32_e32 v145, 0x45800000, v134
	v_cndmask_b32_e32 v134, v134, v145, vcc
	v_mul_f32_e32 v154, 0x3e16c740, v134
	v_pk_mul_f32 v[128:129], v[128:129], v[154:155] op_sel_hi:[1,0]
	v_pk_mul_f32 v[126:127], v[126:127], v[154:155] op_sel_hi:[1,0]
	v_pk_mul_f32 v[156:157], v[124:125], v[154:155] op_sel_hi:[1,0]
	v_pk_mul_f32 v[158:159], v[122:123], v[154:155] op_sel_hi:[1,0]
	s_cbranch_scc1 .LBB0_298
	s_waitcnt vmcnt(0)
	v_mov_b32_e32 v122, v248
	v_mov_b32_e32 v123, v249
	v_mov_b32_e32 v124, v250
	v_mov_b32_e32 v125, v251
	v_mov_b32_e32 v168, v252
	v_mov_b32_e32 v169, v253
	v_mov_b32_e32 v170, v254
	v_mov_b32_e32 v171, v255
	v_lshl_add_u64 v[246:247], v[246:247], 0, s[96:97]
	global_load_dwordx4 v[248:251], v[246:247], off offset:64
	global_load_dwordx4 v[252:255], v[246:247], off
	v_pk_mul_f32 v[172:173], v[156:157], v[124:125]
	v_pk_mul_f32 v[174:175], v[158:159], v[122:123]
	v_pk_mul_f32 v[124:125], v[128:129], v[124:125]
	v_pk_mul_f32 v[122:123], v[126:127], v[122:123]
	v_pk_fma_f32 v[128:129], v[128:129], v[170:171], v[172:173] neg_lo:[0,0,1] neg_hi:[0,0,1]
	v_pk_fma_f32 v[126:127], v[126:127], v[168:169], v[174:175] neg_lo:[0,0,1] neg_hi:[0,0,1]
	v_pk_fma_f32 v[156:157], v[156:157], v[170:171], v[124:125]
	v_pk_fma_f32 v[158:159], v[158:159], v[168:169], v[122:123]
; #define GAS __attribute__((address_space(1)))
;   DI void operator()(const acc_t& acc, const Unit& u, int, int, int, int) const {
;     ...
;     for (int ai = 0; ai < 2; ++ai)
; #pragma unroll
;       for (int m = 0; m < 4; ++m) {
;         const int row = row0 + ai * 128 + m * 16;
;         const float r = rsqrtf((cqss[row] + cqss[NTOK + row]) * (1.f / 384.f) + EPS) * QS_MLA;
;         const int ridx = samp ? 2048 + ((row - NTOK_P) & 63) : (row & 2047);
; #pragma unroll
;         for (int bj = 0; bj < 2; ++bj) {
;           const int gi = u.pn * 8 + bj * 4 + wc;
;           f32x4 x1 = acc[ai][bj][m][0] * r, x2 = acc[ai][bj][m][1] * r;
;           if (gi % 3 == 2) {
;             const f32x4 cs = *(const GAS f32x4*)(tab + ridx * 32 + 4 * fq), sn = *(const GAS f32x4*)(tab + ridx * 32 + 16 + 4 * fq);
;             const f32x4 o1 = x1 * cs - x2 * sn, o2 = x2 * cs + x1 * sn;
;             x1 = o1; x2 = o2;
;           }
;           GAS u16* rp = dst + (size_t)row * 768 + gi * 32 + 4 * fq;
;           *(GAS u32x2*)(rp) = (u32x2){pk2(x1.x, x1.y), pk2(x1.z, x1.w)};
;           *(GAS u32x2*)(rp + 16) = (u32x2){pk2(x2.x, x2.y), pk2(x2.z, x2.w)};
;         }
.LBB0_298:
	v_lshlrev_b32_e32 v134, 1, v147
	v_lshl_add_u64 v[122:123], s[4:5], 0, v[134:135]
	v_lshl_add_u64 v[122:123], v[122:123], 0, s[22:23]
	v_mad_i64_i32 v[124:125], s[4:5], v146, s68, v[122:123]
	s_or_b32 s4, s6, 4
	s_mul_hi_i32 s5, s4, 0x55555556
	s_lshl_b32 s36, s6, 5
	s_lshr_b32 s6, s5, 31
	s_ashr_i32 s37, s36, 31
	s_add_i32 s5, s5, s6
	v_lshl_add_u64 v[168:169], s[36:37], 1, v[124:125]
	v_cvt_pk_bf16_f32 v126, v126, v127
	v_cvt_pk_bf16_f32 v127, v128, v129
	s_mul_i32 s5, s5, 3
	global_store_dwordx2 v[168:169], v[126:127], off
	v_cvt_pk_bf16_f32 v126, v158, v159
	v_cvt_pk_bf16_f32 v127, v156, v157
	s_sub_i32 s5, s4, s5
	v_mov_b32_e32 v155, v154
	global_store_dwordx2 v[168:169], v[126:127], off offset:32
	v_mov_b32_e32 v126, v154
	v_mov_b32_e32 v127, v154
	s_cmp_eq_u32 s5, 2
	v_pk_mul_f32 v[120:121], v[120:121], v[126:127]
	v_pk_mul_f32 v[118:119], v[118:119], v[154:155]
	v_pk_mul_f32 v[116:117], v[116:117], v[126:127]
	s_cselect_b64 s[42:43], -1, 0
	s_cmp_lg_u32 s5, 2
	v_pk_mul_f32 v[114:115], v[114:115], v[154:155]
	s_cbranch_scc1 .LBB0_300
	s_waitcnt vmcnt(2)
	v_mov_b32_e32 v126, v248
	v_mov_b32_e32 v127, v249
	v_mov_b32_e32 v128, v250
	v_mov_b32_e32 v129, v251
	v_mov_b32_e32 v152, v252
	v_mov_b32_e32 v153, v253
	v_mov_b32_e32 v154, v254
	v_mov_b32_e32 v155, v255
	v_lshl_add_u64 v[246:247], v[246:247], 0, s[96:97]
	global_load_dwordx4 v[248:251], v[246:247], off offset:64
	global_load_dwordx4 v[252:255], v[246:247], off
	v_pk_mul_f32 v[156:157], v[116:117], v[128:129]
	v_pk_mul_f32 v[158:159], v[114:115], v[126:127]
	v_pk_mul_f32 v[128:129], v[120:121], v[128:129]
	v_pk_mul_f32 v[126:127], v[118:119], v[126:127]
	v_pk_fma_f32 v[120:121], v[120:121], v[154:155], v[156:157] neg_lo:[0,0,1] neg_hi:[0,0,1]
	v_pk_fma_f32 v[118:119], v[118:119], v[152:153], v[158:159] neg_lo:[0,0,1] neg_hi:[0,0,1]
	v_pk_fma_f32 v[116:117], v[116:117], v[154:155], v[128:129]
	v_pk_fma_f32 v[114:115], v[114:115], v[152:153], v[126:127]
.LBB0_300:
	s_lshl_b32 s38, s4, 5
	s_ashr_i32 s39, s38, 31
	v_lshl_add_u64 v[124:125], s[38:39], 1, v[124:125]
	v_cvt_pk_bf16_f32 v118, v118, v119
	v_cvt_pk_bf16_f32 v119, v120, v121
	v_cvt_pk_bf16_f32 v114, v114, v115
	v_cvt_pk_bf16_f32 v115, v116, v117
	global_store_dwordx2 v[124:125], v[118:119], off
	global_store_dwordx2 v[124:125], v[114:115], off offset:32
	v_or_b32_e32 v114, 16, v146
	v_ashrrev_i32_e32 v115, 31, v114
	v_lshl_add_u64 v[116:117], v[114:115], 2, s[40:41]
	v_add_co_u32_e32 v118, vcc, s66, v116
	v_or_b32_e32 v115, 0x810, v166
	s_nop 0
	v_addc_co_u32_e32 v119, vcc, 0, v117, vcc
	v_mov_b32_e32 v116, v232
	s_nop 0
	v_mov_b32_e32 v117, v233
	v_bitop3_b32 v118, v146, s69, 16 bitop3:0xc8
	v_cndmask_b32_e64 v118, v118, v115, s[8:9]
	v_lshlrev_b32_e32 v134, 7, v118
	v_cndmask_b32_e64 v119, 0, 1, s[10:11]
	v_cmp_ne_u32_e64 s[6:7], 1, v119
	v_mov_b32_e32 v145, v135
	s_andn2_b64 vcc, exec, s[10:11]
	s_nop 0
	v_add_f32_e32 v116, v116, v117
	v_fmamk_f32 v116, v116, 0x3b2aaaab, v164
	v_mul_f32_e32 v117, 0x4b800000, v116
	v_cmp_gt_f32_e64 s[4:5], s67, v116
	s_nop 1
	v_cndmask_b32_e64 v116, v116, v117, s[4:5]
	v_rsq_f32_e32 v118, v116
	v_lshl_add_u64 v[116:117], s[34:35], 0, v[134:135]
	v_lshl_add_u64 v[116:117], v[116:117], 0, v[144:145]
	v_mul_f32_e32 v119, 0x45800000, v118
	v_cndmask_b32_e64 v118, v118, v119, s[4:5]
	v_mul_f32_e32 v118, 0x3e16c740, v118
	v_pk_mul_f32 v[112:113], v[112:113], v[118:119] op_sel_hi:[1,0]
	v_pk_mul_f32 v[110:111], v[110:111], v[118:119] op_sel_hi:[1,0]
	v_pk_mul_f32 v[108:109], v[108:109], v[118:119] op_sel_hi:[1,0]
	v_pk_mul_f32 v[120:121], v[106:107], v[118:119] op_sel_hi:[1,0]
	s_cbranch_vccnz .LBB0_302
	s_waitcnt vmcnt(4)
	v_mov_b32_e32 v124, v248
	v_mov_b32_e32 v125, v249
	v_mov_b32_e32 v126, v250
	v_mov_b32_e32 v127, v251
	v_mov_b32_e32 v152, v252
	v_mov_b32_e32 v153, v253
	v_mov_b32_e32 v154, v254
	v_mov_b32_e32 v155, v255
	v_lshl_add_u64 v[246:247], v[246:247], 0, s[96:97]
	global_load_dwordx4 v[248:251], v[246:247], off offset:64
	global_load_dwordx4 v[252:255], v[246:247], off
	v_pk_mul_f32 v[106:107], v[108:109], v[126:127]
	v_pk_mul_f32 v[128:129], v[120:121], v[124:125]
	v_pk_mul_f32 v[126:127], v[112:113], v[126:127]
	v_pk_mul_f32 v[124:125], v[110:111], v[124:125]
	v_pk_fma_f32 v[112:113], v[112:113], v[154:155], v[106:107] neg_lo:[0,0,1] neg_hi:[0,0,1]
	v_pk_fma_f32 v[110:111], v[110:111], v[152:153], v[128:129] neg_lo:[0,0,1] neg_hi:[0,0,1]
	v_pk_fma_f32 v[108:109], v[108:109], v[154:155], v[126:127]
	v_pk_fma_f32 v[120:121], v[120:121], v[152:153], v[124:125]
.LBB0_302:
	v_mad_i64_i32 v[106:107], s[4:5], v114, s68, v[122:123]
	v_lshl_add_u64 v[124:125], s[36:37], 1, v[106:107]
	v_cvt_pk_bf16_f32 v110, v110, v111
	v_cvt_pk_bf16_f32 v111, v112, v113
	global_store_dwordx2 v[124:125], v[110:111], off
	v_cvt_pk_bf16_f32 v111, v108, v109
	v_mov_b32_e32 v108, v118
	v_mov_b32_e32 v109, v118
	v_mov_b32_e32 v119, v118
	v_pk_mul_f32 v[104:105], v[104:105], v[108:109]
	v_pk_mul_f32 v[100:101], v[100:101], v[108:109]
	v_cndmask_b32_e64 v108, 0, 1, s[42:43]
	v_cvt_pk_bf16_f32 v110, v120, v121
	v_pk_mul_f32 v[102:103], v[102:103], v[118:119]
	v_cmp_ne_u32_e64 s[4:5], 1, v108
	s_andn2_b64 vcc, exec, s[42:43]
	v_pk_mul_f32 v[98:99], v[98:99], v[118:119]
	global_store_dwordx2 v[124:125], v[110:111], off offset:32
	s_cbranch_vccnz .LBB0_304
	s_waitcnt vmcnt(4)
	v_mov_b32_e32 v108, v248
	v_mov_b32_e32 v109, v249
	v_mov_b32_e32 v110, v250
	v_mov_b32_e32 v111, v251
	v_mov_b32_e32 v116, v252
	v_mov_b32_e32 v117, v253
	v_mov_b32_e32 v118, v254
	v_mov_b32_e32 v119, v255
	v_lshl_add_u64 v[246:247], v[246:247], 0, s[96:97]
	global_load_dwordx4 v[248:251], v[246:247], off offset:64
	global_load_dwordx4 v[252:255], v[246:247], off
	v_pk_mul_f32 v[112:113], v[100:101], v[110:111]
	v_pk_mul_f32 v[120:121], v[98:99], v[108:109]
	v_pk_mul_f32 v[110:111], v[104:105], v[110:111]
	v_pk_mul_f32 v[108:109], v[102:103], v[108:109]
	v_pk_fma_f32 v[104:105], v[104:105], v[118:119], v[112:113] neg_lo:[0,0,1] neg_hi:[0,0,1]
	v_pk_fma_f32 v[102:103], v[102:103], v[116:117], v[120:121] neg_lo:[0,0,1] neg_hi:[0,0,1]
	v_pk_fma_f32 v[100:101], v[100:101], v[118:119], v[110:111]
	v_pk_fma_f32 v[98:99], v[98:99], v[116:117], v[108:109]
; #define GAS __attribute__((address_space(1)))
;   DI void operator()(const acc_t& acc, const Unit& u, int, int, int, int) const {
;     ...
;     for (int ai = 0; ai < 2; ++ai)
; #pragma unroll
;       for (int m = 0; m < 4; ++m) {
;         const int row = row0 + ai * 128 + m * 16;
;         const float r = rsqrtf((cqss[row] + cqss[NTOK + row]) * (1.f / 384.f) + EPS) * QS_MLA;
;         const int ridx = samp ? 2048 + ((row - NTOK_P) & 63) : (row & 2047);
; #pragma unroll
;         for (int bj = 0; bj < 2; ++bj) {
;           const int gi = u.pn * 8 + bj * 4 + wc;
;           f32x4 x1 = acc[ai][bj][m][0] * r, x2 = acc[ai][bj][m][1] * r;
;           if (gi % 3 == 2) {
;             const f32x4 cs = *(const GAS f32x4*)(tab + ridx * 32 + 4 * fq), sn = *(const GAS f32x4*)(tab + ridx * 32 + 16 + 4 * fq);
;             const f32x4 o1 = x1 * cs - x2 * sn, o2 = x2 * cs + x1 * sn;
;             x1 = o1; x2 = o2;
;           }
;           GAS u16* rp = dst + (size_t)row * 768 + gi * 32 + 4 * fq;
;           *(GAS u32x2*)(rp) = (u32x2){pk2(x1.x, x1.y), pk2(x1.z, x1.w)};
;           *(GAS u32x2*)(rp + 16) = (u32x2){pk2(x2.x, x2.y), pk2(x2.z, x2.w)};
;         }
.LBB0_304:
	v_lshl_add_u64 v[106:107], s[38:39], 1, v[106:107]
	v_cvt_pk_bf16_f32 v102, v102, v103
	v_cvt_pk_bf16_f32 v103, v104, v105
	v_cvt_pk_bf16_f32 v98, v98, v99
	v_cvt_pk_bf16_f32 v99, v100, v101
	global_store_dwordx2 v[106:107], v[102:103], off
	global_store_dwordx2 v[106:107], v[98:99], off offset:32
	v_or_b32_e32 v98, 32, v146
	v_ashrrev_i32_e32 v99, 31, v98
	v_lshl_add_u64 v[100:101], v[98:99], 2, s[40:41]
	v_add_co_u32_e32 v102, vcc, s66, v100
	v_or_b32_e32 v99, 0x820, v166
	s_nop 0
	v_addc_co_u32_e32 v103, vcc, 0, v101, vcc
	v_mov_b32_e32 v100, v234
	s_nop 0
	v_mov_b32_e32 v101, v235
	v_bitop3_b32 v102, v146, s70, 32 bitop3:0xc8
	v_cndmask_b32_e64 v102, v102, v99, s[8:9]
	v_lshlrev_b32_e32 v134, 7, v102
	v_mov_b32_e32 v145, v135
	s_and_b64 vcc, exec, s[6:7]
	s_nop 0
	v_add_f32_e32 v100, v100, v101
	v_fmamk_f32 v100, v100, 0x3b2aaaab, v164
	v_mul_f32_e32 v101, 0x4b800000, v100
	v_cmp_gt_f32_e64 s[10:11], s67, v100
	s_nop 1
	v_cndmask_b32_e64 v100, v100, v101, s[10:11]
	v_rsq_f32_e32 v103, v100
	v_lshl_add_u64 v[100:101], s[34:35], 0, v[134:135]
	v_lshl_add_u64 v[100:101], v[100:101], 0, v[144:145]
	v_mul_f32_e32 v102, 0x45800000, v103
	v_cndmask_b32_e64 v102, v103, v102, s[10:11]
	v_mul_f32_e32 v102, 0x3e16c740, v102
	v_pk_mul_f32 v[96:97], v[96:97], v[102:103] op_sel_hi:[1,0]
	v_pk_mul_f32 v[94:95], v[94:95], v[102:103] op_sel_hi:[1,0]
	v_pk_mul_f32 v[92:93], v[92:93], v[102:103] op_sel_hi:[1,0]
	v_pk_mul_f32 v[104:105], v[90:91], v[102:103] op_sel_hi:[1,0]
	s_cbranch_vccnz .LBB0_306
	s_waitcnt vmcnt(4)
	v_mov_b32_e32 v106, v248
	v_mov_b32_e32 v107, v249
	v_mov_b32_e32 v108, v250
	v_mov_b32_e32 v109, v251
	v_mov_b32_e32 v110, v252
	v_mov_b32_e32 v111, v253
	v_mov_b32_e32 v112, v254
	v_mov_b32_e32 v113, v255
	v_lshl_add_u64 v[246:247], v[246:247], 0, s[96:97]
	global_load_dwordx4 v[248:251], v[246:247], off offset:64
	global_load_dwordx4 v[252:255], v[246:247], off
	v_pk_mul_f32 v[90:91], v[92:93], v[108:109]
	v_pk_mul_f32 v[116:117], v[104:105], v[106:107]
	v_pk_mul_f32 v[108:109], v[96:97], v[108:109]
	v_pk_mul_f32 v[106:107], v[94:95], v[106:107]
	v_pk_fma_f32 v[96:97], v[96:97], v[112:113], v[90:91] neg_lo:[0,0,1] neg_hi:[0,0,1]
	v_pk_fma_f32 v[94:95], v[94:95], v[110:111], v[116:117] neg_lo:[0,0,1] neg_hi:[0,0,1]
	v_pk_fma_f32 v[92:93], v[92:93], v[112:113], v[108:109]
	v_pk_fma_f32 v[104:105], v[104:105], v[110:111], v[106:107]
.LBB0_306:
	v_mad_i64_i32 v[90:91], s[10:11], v98, s68, v[122:123]
	v_lshl_add_u64 v[106:107], s[36:37], 1, v[90:91]
	v_cvt_pk_bf16_f32 v94, v94, v95
	v_cvt_pk_bf16_f32 v95, v96, v97
	v_mov_b32_e32 v103, v102
	global_store_dwordx2 v[106:107], v[94:95], off
	v_cvt_pk_bf16_f32 v95, v92, v93
	v_mov_b32_e32 v92, v102
	v_mov_b32_e32 v93, v102
	v_cvt_pk_bf16_f32 v94, v104, v105
	v_pk_mul_f32 v[88:89], v[88:89], v[92:93]
	v_pk_mul_f32 v[86:87], v[86:87], v[102:103]
	v_pk_mul_f32 v[84:85], v[84:85], v[92:93]
	s_and_b64 vcc, exec, s[4:5]
	v_pk_mul_f32 v[82:83], v[82:83], v[102:103]
	global_store_dwordx2 v[106:107], v[94:95], off offset:32
	s_cbranch_vccnz .LBB0_308
	s_waitcnt vmcnt(4)
	v_mov_b32_e32 v92, v248
	v_mov_b32_e32 v93, v249
	v_mov_b32_e32 v94, v250
	v_mov_b32_e32 v95, v251
	v_mov_b32_e32 v100, v252
	v_mov_b32_e32 v101, v253
	v_mov_b32_e32 v102, v254
	v_mov_b32_e32 v103, v255
	v_lshl_add_u64 v[246:247], v[246:247], 0, s[96:97]
	global_load_dwordx4 v[248:251], v[246:247], off offset:64
	global_load_dwordx4 v[252:255], v[246:247], off
	v_pk_mul_f32 v[96:97], v[84:85], v[94:95]
	v_pk_mul_f32 v[104:105], v[82:83], v[92:93]
	v_pk_mul_f32 v[94:95], v[88:89], v[94:95]
	v_pk_mul_f32 v[92:93], v[86:87], v[92:93]
	v_pk_fma_f32 v[88:89], v[88:89], v[102:103], v[96:97] neg_lo:[0,0,1] neg_hi:[0,0,1]
	v_pk_fma_f32 v[86:87], v[86:87], v[100:101], v[104:105] neg_lo:[0,0,1] neg_hi:[0,0,1]
	v_pk_fma_f32 v[84:85], v[84:85], v[102:103], v[94:95]
	v_pk_fma_f32 v[82:83], v[82:83], v[100:101], v[92:93]
.LBB0_308:
	v_lshl_add_u64 v[90:91], s[38:39], 1, v[90:91]
	v_cvt_pk_bf16_f32 v86, v86, v87
	v_cvt_pk_bf16_f32 v87, v88, v89
	v_cvt_pk_bf16_f32 v82, v82, v83
	v_cvt_pk_bf16_f32 v83, v84, v85
	global_store_dwordx2 v[90:91], v[86:87], off
	global_store_dwordx2 v[90:91], v[82:83], off offset:32
	v_or_b32_e32 v82, 48, v146
	v_ashrrev_i32_e32 v83, 31, v82
	v_lshl_add_u64 v[84:85], v[82:83], 2, s[40:41]
	v_add_co_u32_e32 v86, vcc, s66, v84
	v_or_b32_e32 v83, 0x830, v166
	s_nop 0
	v_addc_co_u32_e32 v87, vcc, 0, v85, vcc
	v_mov_b32_e32 v84, v236
	s_nop 0
	v_mov_b32_e32 v85, v237
	v_bitop3_b32 v86, v146, s71, 48 bitop3:0xc8
	v_cndmask_b32_e64 v86, v86, v83, s[8:9]
	v_lshlrev_b32_e32 v134, 7, v86
	v_mov_b32_e32 v145, v135
	s_and_b64 vcc, exec, s[6:7]
	s_nop 0
	v_add_f32_e32 v84, v84, v85
	v_fmamk_f32 v84, v84, 0x3b2aaaab, v164
	v_mul_f32_e32 v85, 0x4b800000, v84
	v_cmp_gt_f32_e64 s[10:11], s67, v84
	s_nop 1
	v_cndmask_b32_e64 v84, v84, v85, s[10:11]
	v_rsq_f32_e32 v87, v84
	v_lshl_add_u64 v[84:85], s[34:35], 0, v[134:135]
	v_lshl_add_u64 v[84:85], v[84:85], 0, v[144:145]
	v_mul_f32_e32 v86, 0x45800000, v87
	v_cndmask_b32_e64 v86, v87, v86, s[10:11]
	v_mul_f32_e32 v86, 0x3e16c740, v86
	v_pk_mul_f32 v[80:81], v[80:81], v[86:87] op_sel_hi:[1,0]
	v_pk_mul_f32 v[78:79], v[78:79], v[86:87] op_sel_hi:[1,0]
	v_pk_mul_f32 v[76:77], v[76:77], v[86:87] op_sel_hi:[1,0]
	v_pk_mul_f32 v[88:89], v[74:75], v[86:87] op_sel_hi:[1,0]
	s_cbranch_vccnz .LBB0_310
	s_waitcnt vmcnt(4)
	v_mov_b32_e32 v90, v248
	v_mov_b32_e32 v91, v249
	v_mov_b32_e32 v92, v250
	v_mov_b32_e32 v93, v251
	v_mov_b32_e32 v94, v252
	v_mov_b32_e32 v95, v253
	v_mov_b32_e32 v96, v254
	v_mov_b32_e32 v97, v255
	v_lshl_add_u64 v[246:247], v[246:247], 0, s[98:99]
	global_load_dwordx4 v[248:251], v[246:247], off offset:64
	global_load_dwordx4 v[252:255], v[246:247], off
	v_pk_mul_f32 v[74:75], v[76:77], v[92:93]
	v_pk_mul_f32 v[100:101], v[88:89], v[90:91]
	v_pk_mul_f32 v[92:93], v[80:81], v[92:93]
	v_pk_mul_f32 v[90:91], v[78:79], v[90:91]
	v_pk_fma_f32 v[80:81], v[80:81], v[96:97], v[74:75] neg_lo:[0,0,1] neg_hi:[0,0,1]
	v_pk_fma_f32 v[78:79], v[78:79], v[94:95], v[100:101] neg_lo:[0,0,1] neg_hi:[0,0,1]
	v_pk_fma_f32 v[76:77], v[76:77], v[96:97], v[92:93]
	v_pk_fma_f32 v[88:89], v[88:89], v[94:95], v[90:91]
; #define GAS __attribute__((address_space(1)))
;   DI void operator()(const acc_t& acc, const Unit& u, int, int, int, int) const {
;     ...
;     for (int ai = 0; ai < 2; ++ai)
; #pragma unroll
;       for (int m = 0; m < 4; ++m) {
;         const int row = row0 + ai * 128 + m * 16;
;         const float r = rsqrtf((cqss[row] + cqss[NTOK + row]) * (1.f / 384.f) + EPS) * QS_MLA;
;         const int ridx = samp ? 2048 + ((row - NTOK_P) & 63) : (row & 2047);
; #pragma unroll
;         for (int bj = 0; bj < 2; ++bj) {
;           const int gi = u.pn * 8 + bj * 4 + wc;
;           f32x4 x1 = acc[ai][bj][m][0] * r, x2 = acc[ai][bj][m][1] * r;
;           if (gi % 3 == 2) {
;             const f32x4 cs = *(const GAS f32x4*)(tab + ridx * 32 + 4 * fq), sn = *(const GAS f32x4*)(tab + ridx * 32 + 16 + 4 * fq);
;             const f32x4 o1 = x1 * cs - x2 * sn, o2 = x2 * cs + x1 * sn;
;             x1 = o1; x2 = o2;
;           }
;           GAS u16* rp = dst + (size_t)row * 768 + gi * 32 + 4 * fq;
;           *(GAS u32x2*)(rp) = (u32x2){pk2(x1.x, x1.y), pk2(x1.z, x1.w)};
;           *(GAS u32x2*)(rp + 16) = (u32x2){pk2(x2.x, x2.y), pk2(x2.z, x2.w)};
;         }
.LBB0_310:
	v_mad_i64_i32 v[74:75], s[10:11], v82, s68, v[122:123]
	v_lshl_add_u64 v[90:91], s[36:37], 1, v[74:75]
	v_cvt_pk_bf16_f32 v78, v78, v79
	v_cvt_pk_bf16_f32 v79, v80, v81
	v_mov_b32_e32 v87, v86
	global_store_dwordx2 v[90:91], v[78:79], off
	v_cvt_pk_bf16_f32 v79, v76, v77
	v_mov_b32_e32 v76, v86
	v_mov_b32_e32 v77, v86
	v_cvt_pk_bf16_f32 v78, v88, v89
	v_pk_mul_f32 v[72:73], v[72:73], v[76:77]
	v_pk_mul_f32 v[70:71], v[70:71], v[86:87]
	v_pk_mul_f32 v[68:69], v[68:69], v[76:77]
	s_and_b64 vcc, exec, s[4:5]
	v_pk_mul_f32 v[66:67], v[66:67], v[86:87]
	global_store_dwordx2 v[90:91], v[78:79], off offset:32
	s_cbranch_vccnz .LBB0_312
	s_waitcnt vmcnt(4)
	v_mov_b32_e32 v76, v248
	v_mov_b32_e32 v77, v249
	v_mov_b32_e32 v78, v250
	v_mov_b32_e32 v79, v251
	v_mov_b32_e32 v84, v252
	v_mov_b32_e32 v85, v253
	v_mov_b32_e32 v86, v254
	v_mov_b32_e32 v87, v255
	v_lshl_add_u64 v[246:247], v[246:247], 0, s[98:99]
	global_load_dwordx4 v[248:251], v[246:247], off offset:64
	global_load_dwordx4 v[252:255], v[246:247], off
	v_pk_mul_f32 v[80:81], v[68:69], v[78:79]
	v_pk_mul_f32 v[88:89], v[66:67], v[76:77]
	v_pk_mul_f32 v[78:79], v[72:73], v[78:79]
	v_pk_mul_f32 v[76:77], v[70:71], v[76:77]
	v_pk_fma_f32 v[72:73], v[72:73], v[86:87], v[80:81] neg_lo:[0,0,1] neg_hi:[0,0,1]
	v_pk_fma_f32 v[70:71], v[70:71], v[84:85], v[88:89] neg_lo:[0,0,1] neg_hi:[0,0,1]
	v_pk_fma_f32 v[68:69], v[68:69], v[86:87], v[78:79]
	v_pk_fma_f32 v[66:67], v[66:67], v[84:85], v[76:77]
.LBB0_312:
	v_lshl_add_u64 v[74:75], s[38:39], 1, v[74:75]
	v_cvt_pk_bf16_f32 v70, v70, v71
	v_cvt_pk_bf16_f32 v71, v72, v73
	v_cvt_pk_bf16_f32 v66, v66, v67
	v_cvt_pk_bf16_f32 v67, v68, v69
	global_store_dwordx2 v[74:75], v[70:71], off
	global_store_dwordx2 v[74:75], v[66:67], off offset:32
	v_mov_b32_e32 v66, v238
	s_nop 0
	v_mov_b32_e32 v67, v239
	v_add_u32_e32 v72, 0x80, v146
	v_and_b32_e32 v68, 0x7cf, v72
	v_cndmask_b32_e64 v68, v68, v165, s[8:9]
	v_lshlrev_b32_e32 v134, 7, v68
	v_mov_b32_e32 v145, v135
	s_and_b64 vcc, exec, s[6:7]
	s_nop 0
	v_add_f32_e32 v66, v66, v67
	v_fmamk_f32 v66, v66, 0x3b2aaaab, v164
	v_mul_f32_e32 v67, 0x4b800000, v66
	v_cmp_gt_f32_e64 s[10:11], s67, v66
	s_nop 1
	v_cndmask_b32_e64 v66, v66, v67, s[10:11]
	v_rsq_f32_e32 v69, v66
	v_lshl_add_u64 v[66:67], s[34:35], 0, v[134:135]
	v_lshl_add_u64 v[66:67], v[66:67], 0, v[144:145]
	v_mul_f32_e32 v68, 0x45800000, v69
	v_cndmask_b32_e64 v68, v69, v68, s[10:11]
	v_mul_f32_e32 v68, 0x3e16c740, v68
	v_pk_mul_f32 v[64:65], v[64:65], v[68:69] op_sel_hi:[1,0]
	v_pk_mul_f32 v[62:63], v[62:63], v[68:69] op_sel_hi:[1,0]
	v_pk_mul_f32 v[60:61], v[60:61], v[68:69] op_sel_hi:[1,0]
	v_pk_mul_f32 v[70:71], v[58:59], v[68:69] op_sel_hi:[1,0]
	s_cbranch_vccnz .LBB0_314
	s_waitcnt vmcnt(4)
	v_mov_b32_e32 v74, v248
	v_mov_b32_e32 v75, v249
	v_mov_b32_e32 v76, v250
	v_mov_b32_e32 v77, v251
	v_mov_b32_e32 v78, v252
	v_mov_b32_e32 v79, v253
	v_mov_b32_e32 v80, v254
	v_mov_b32_e32 v81, v255
	v_lshl_add_u64 v[246:247], v[246:247], 0, s[96:97]
	global_load_dwordx4 v[248:251], v[246:247], off offset:64
	global_load_dwordx4 v[252:255], v[246:247], off
	v_pk_mul_f32 v[58:59], v[60:61], v[76:77]
	v_pk_mul_f32 v[84:85], v[70:71], v[74:75]
	v_pk_mul_f32 v[76:77], v[64:65], v[76:77]
	v_pk_mul_f32 v[74:75], v[62:63], v[74:75]
	v_pk_fma_f32 v[64:65], v[64:65], v[80:81], v[58:59] neg_lo:[0,0,1] neg_hi:[0,0,1]
	v_pk_fma_f32 v[62:63], v[62:63], v[78:79], v[84:85] neg_lo:[0,0,1] neg_hi:[0,0,1]
	v_pk_fma_f32 v[60:61], v[60:61], v[80:81], v[76:77]
	v_pk_fma_f32 v[70:71], v[70:71], v[78:79], v[74:75]
.LBB0_314:
	v_mad_i64_i32 v[58:59], s[10:11], v72, s68, v[122:123]
	v_lshl_add_u64 v[72:73], s[36:37], 1, v[58:59]
	v_cvt_pk_bf16_f32 v62, v62, v63
	v_cvt_pk_bf16_f32 v63, v64, v65
	v_mov_b32_e32 v69, v68
	global_store_dwordx2 v[72:73], v[62:63], off
	v_cvt_pk_bf16_f32 v63, v60, v61
	v_mov_b32_e32 v60, v68
	v_mov_b32_e32 v61, v68
	v_cvt_pk_bf16_f32 v62, v70, v71
	v_pk_mul_f32 v[56:57], v[56:57], v[60:61]
	v_pk_mul_f32 v[54:55], v[54:55], v[68:69]
	v_pk_mul_f32 v[52:53], v[52:53], v[60:61]
	s_and_b64 vcc, exec, s[4:5]
	v_pk_mul_f32 v[50:51], v[50:51], v[68:69]
	global_store_dwordx2 v[72:73], v[62:63], off offset:32
	s_cbranch_vccnz .LBB0_316
	s_waitcnt vmcnt(4)
	v_mov_b32_e32 v60, v248
	v_mov_b32_e32 v61, v249
	v_mov_b32_e32 v62, v250
	v_mov_b32_e32 v63, v251
	v_mov_b32_e32 v64, v252
	v_mov_b32_e32 v65, v253
	v_mov_b32_e32 v66, v254
	v_mov_b32_e32 v67, v255
	v_lshl_add_u64 v[246:247], v[246:247], 0, s[96:97]
	global_load_dwordx4 v[248:251], v[246:247], off offset:64
	global_load_dwordx4 v[252:255], v[246:247], off
	v_pk_mul_f32 v[68:69], v[52:53], v[62:63]
	v_pk_mul_f32 v[70:71], v[50:51], v[60:61]
	v_pk_mul_f32 v[62:63], v[56:57], v[62:63]
	v_pk_mul_f32 v[60:61], v[54:55], v[60:61]
	v_pk_fma_f32 v[56:57], v[56:57], v[66:67], v[68:69] neg_lo:[0,0,1] neg_hi:[0,0,1]
	v_pk_fma_f32 v[54:55], v[54:55], v[64:65], v[70:71] neg_lo:[0,0,1] neg_hi:[0,0,1]
	v_pk_fma_f32 v[52:53], v[52:53], v[66:67], v[62:63]
	v_pk_fma_f32 v[50:51], v[50:51], v[64:65], v[60:61]
; #define GAS __attribute__((address_space(1)))
;   DI void operator()(const acc_t& acc, const Unit& u, int, int, int, int) const {
;     ...
;     for (int ai = 0; ai < 2; ++ai)
; #pragma unroll
;       for (int m = 0; m < 4; ++m) {
;         const int row = row0 + ai * 128 + m * 16;
;         const float r = rsqrtf((cqss[row] + cqss[NTOK + row]) * (1.f / 384.f) + EPS) * QS_MLA;
;         const int ridx = samp ? 2048 + ((row - NTOK_P) & 63) : (row & 2047);
; #pragma unroll
;         for (int bj = 0; bj < 2; ++bj) {
;           const int gi = u.pn * 8 + bj * 4 + wc;
;           f32x4 x1 = acc[ai][bj][m][0] * r, x2 = acc[ai][bj][m][1] * r;
;           if (gi % 3 == 2) {
;             const f32x4 cs = *(const GAS f32x4*)(tab + ridx * 32 + 4 * fq), sn = *(const GAS f32x4*)(tab + ridx * 32 + 16 + 4 * fq);
;             const f32x4 o1 = x1 * cs - x2 * sn, o2 = x2 * cs + x1 * sn;
;             x1 = o1; x2 = o2;
;           }
;           GAS u16* rp = dst + (size_t)row * 768 + gi * 32 + 4 * fq;
;           *(GAS u32x2*)(rp) = (u32x2){pk2(x1.x, x1.y), pk2(x1.z, x1.w)};
;           *(GAS u32x2*)(rp + 16) = (u32x2){pk2(x2.x, x2.y), pk2(x2.z, x2.w)};
;         }
.LBB0_316:
	v_lshl_add_u64 v[58:59], s[38:39], 1, v[58:59]
	v_cvt_pk_bf16_f32 v54, v54, v55
	v_cvt_pk_bf16_f32 v55, v56, v57
	v_cvt_pk_bf16_f32 v50, v50, v51
	v_cvt_pk_bf16_f32 v51, v52, v53
	global_store_dwordx2 v[58:59], v[54:55], off
	global_store_dwordx2 v[58:59], v[50:51], off offset:32
	v_mov_b32_e32 v50, v240
	s_nop 0
	v_mov_b32_e32 v51, v241
	v_add_u32_e32 v56, 0x90, v146
	v_and_b32_e32 v52, 0x7df, v56
	v_cndmask_b32_e64 v52, v52, v115, s[8:9]
	v_lshlrev_b32_e32 v134, 7, v52
	v_mov_b32_e32 v145, v135
	s_and_b64 vcc, exec, s[6:7]
	s_nop 0
	v_add_f32_e32 v50, v50, v51
	v_fmamk_f32 v50, v50, 0x3b2aaaab, v164
	v_mul_f32_e32 v51, 0x4b800000, v50
	v_cmp_gt_f32_e64 s[10:11], s67, v50
	s_nop 1
	v_cndmask_b32_e64 v50, v50, v51, s[10:11]
	v_rsq_f32_e32 v53, v50
	v_lshl_add_u64 v[50:51], s[34:35], 0, v[134:135]
	v_lshl_add_u64 v[50:51], v[50:51], 0, v[144:145]
	v_mul_f32_e32 v52, 0x45800000, v53
	v_cndmask_b32_e64 v52, v53, v52, s[10:11]
	v_mul_f32_e32 v52, 0x3e16c740, v52
	v_pk_mul_f32 v[48:49], v[48:49], v[52:53] op_sel_hi:[1,0]
	v_pk_mul_f32 v[46:47], v[46:47], v[52:53] op_sel_hi:[1,0]
	v_pk_mul_f32 v[44:45], v[44:45], v[52:53] op_sel_hi:[1,0]
	v_pk_mul_f32 v[54:55], v[42:43], v[52:53] op_sel_hi:[1,0]
	s_cbranch_vccnz .LBB0_318
	s_waitcnt vmcnt(4)
	v_mov_b32_e32 v58, v248
	v_mov_b32_e32 v59, v249
	v_mov_b32_e32 v60, v250
	v_mov_b32_e32 v61, v251
	v_mov_b32_e32 v62, v252
	v_mov_b32_e32 v63, v253
	v_mov_b32_e32 v64, v254
	v_mov_b32_e32 v65, v255
	v_lshl_add_u64 v[246:247], v[246:247], 0, s[96:97]
	global_load_dwordx4 v[248:251], v[246:247], off offset:64
	global_load_dwordx4 v[252:255], v[246:247], off
	v_pk_mul_f32 v[42:43], v[44:45], v[60:61]
	v_pk_mul_f32 v[66:67], v[54:55], v[58:59]
	v_pk_mul_f32 v[60:61], v[48:49], v[60:61]
	v_pk_mul_f32 v[58:59], v[46:47], v[58:59]
	v_pk_fma_f32 v[48:49], v[48:49], v[64:65], v[42:43] neg_lo:[0,0,1] neg_hi:[0,0,1]
	v_pk_fma_f32 v[46:47], v[46:47], v[62:63], v[66:67] neg_lo:[0,0,1] neg_hi:[0,0,1]
	v_pk_fma_f32 v[44:45], v[44:45], v[64:65], v[60:61]
	v_pk_fma_f32 v[54:55], v[54:55], v[62:63], v[58:59]
.LBB0_318:
	v_mad_i64_i32 v[42:43], s[10:11], v56, s68, v[122:123]
	v_lshl_add_u64 v[56:57], s[36:37], 1, v[42:43]
	v_cvt_pk_bf16_f32 v46, v46, v47
	v_cvt_pk_bf16_f32 v47, v48, v49
	v_mov_b32_e32 v53, v52
	global_store_dwordx2 v[56:57], v[46:47], off
	v_cvt_pk_bf16_f32 v47, v44, v45
	v_mov_b32_e32 v44, v52
	v_mov_b32_e32 v45, v52
	v_cvt_pk_bf16_f32 v46, v54, v55
	v_pk_mul_f32 v[40:41], v[40:41], v[44:45]
	v_pk_mul_f32 v[38:39], v[38:39], v[52:53]
	v_pk_mul_f32 v[36:37], v[36:37], v[44:45]
	s_and_b64 vcc, exec, s[4:5]
	v_pk_mul_f32 v[34:35], v[34:35], v[52:53]
	global_store_dwordx2 v[56:57], v[46:47], off offset:32
	s_cbranch_vccnz .LBB0_320
	s_waitcnt vmcnt(4)
	v_mov_b32_e32 v44, v248
	v_mov_b32_e32 v45, v249
	v_mov_b32_e32 v46, v250
	v_mov_b32_e32 v47, v251
	v_mov_b32_e32 v48, v252
	v_mov_b32_e32 v49, v253
	v_mov_b32_e32 v50, v254
	v_mov_b32_e32 v51, v255
	v_lshl_add_u64 v[246:247], v[246:247], 0, s[96:97]
	global_load_dwordx4 v[248:251], v[246:247], off offset:64
	global_load_dwordx4 v[252:255], v[246:247], off
	v_pk_mul_f32 v[52:53], v[36:37], v[46:47]
	v_pk_mul_f32 v[54:55], v[34:35], v[44:45]
	v_pk_mul_f32 v[46:47], v[40:41], v[46:47]
	v_pk_mul_f32 v[44:45], v[38:39], v[44:45]
	v_pk_fma_f32 v[40:41], v[40:41], v[50:51], v[52:53] neg_lo:[0,0,1] neg_hi:[0,0,1]
	v_pk_fma_f32 v[38:39], v[38:39], v[48:49], v[54:55] neg_lo:[0,0,1] neg_hi:[0,0,1]
	v_pk_fma_f32 v[36:37], v[36:37], v[50:51], v[46:47]
	v_pk_fma_f32 v[34:35], v[34:35], v[48:49], v[44:45]
.LBB0_320:
	v_lshl_add_u64 v[42:43], s[38:39], 1, v[42:43]
	v_cvt_pk_bf16_f32 v38, v38, v39
	v_cvt_pk_bf16_f32 v39, v40, v41
	v_cvt_pk_bf16_f32 v34, v34, v35
	v_cvt_pk_bf16_f32 v35, v36, v37
	global_store_dwordx2 v[42:43], v[38:39], off
	global_store_dwordx2 v[42:43], v[34:35], off offset:32
	v_mov_b32_e32 v34, v242
	s_nop 0
	v_mov_b32_e32 v35, v243
	v_add_u32_e32 v40, 0xa0, v146
	v_and_b32_e32 v36, 0x7ef, v40
	v_cndmask_b32_e64 v36, v36, v99, s[8:9]
	v_lshlrev_b32_e32 v134, 7, v36
	v_mov_b32_e32 v145, v135
	s_and_b64 vcc, exec, s[6:7]
	s_nop 0
	v_add_f32_e32 v34, v34, v35
	v_fmamk_f32 v34, v34, 0x3b2aaaab, v164
	v_mul_f32_e32 v35, 0x4b800000, v34
	v_cmp_gt_f32_e64 s[10:11], s67, v34
	s_nop 1
	v_cndmask_b32_e64 v34, v34, v35, s[10:11]
	v_rsq_f32_e32 v37, v34
	v_lshl_add_u64 v[34:35], s[34:35], 0, v[134:135]
	v_lshl_add_u64 v[34:35], v[34:35], 0, v[144:145]
	v_mul_f32_e32 v36, 0x45800000, v37
	v_cndmask_b32_e64 v36, v37, v36, s[10:11]
	v_mul_f32_e32 v36, 0x3e16c740, v36
	v_pk_mul_f32 v[32:33], v[32:33], v[36:37] op_sel_hi:[1,0]
	v_pk_mul_f32 v[30:31], v[30:31], v[36:37] op_sel_hi:[1,0]
	v_pk_mul_f32 v[28:29], v[28:29], v[36:37] op_sel_hi:[1,0]
	v_pk_mul_f32 v[38:39], v[26:27], v[36:37] op_sel_hi:[1,0]
	s_cbranch_vccnz .LBB0_322
	s_waitcnt vmcnt(4)
	v_mov_b32_e32 v42, v248
	v_mov_b32_e32 v43, v249
	v_mov_b32_e32 v44, v250
	v_mov_b32_e32 v45, v251
	v_mov_b32_e32 v46, v252
	v_mov_b32_e32 v47, v253
	v_mov_b32_e32 v48, v254
	v_mov_b32_e32 v49, v255
	v_lshl_add_u64 v[246:247], v[246:247], 0, s[96:97]
	global_load_dwordx4 v[248:251], v[246:247], off offset:64
	global_load_dwordx4 v[252:255], v[246:247], off
	v_pk_mul_f32 v[26:27], v[28:29], v[44:45]
	v_pk_mul_f32 v[50:51], v[38:39], v[42:43]
	v_pk_mul_f32 v[44:45], v[32:33], v[44:45]
	v_pk_mul_f32 v[42:43], v[30:31], v[42:43]
	v_pk_fma_f32 v[32:33], v[32:33], v[48:49], v[26:27] neg_lo:[0,0,1] neg_hi:[0,0,1]
	v_pk_fma_f32 v[30:31], v[30:31], v[46:47], v[50:51] neg_lo:[0,0,1] neg_hi:[0,0,1]
	v_pk_fma_f32 v[28:29], v[28:29], v[48:49], v[44:45]
	v_pk_fma_f32 v[38:39], v[38:39], v[46:47], v[42:43]
; #define GAS __attribute__((address_space(1)))
;   DI void operator()(const acc_t& acc, const Unit& u, int, int, int, int) const {
;     ...
;         const int row = row0 + ai * 128 + m * 16;
;         const float r = rsqrtf((cqss[row] + cqss[NTOK + row]) * (1.f / 384.f) + EPS) * QS_MLA;
;         const int ridx = samp ? 2048 + ((row - NTOK_P) & 63) : (row & 2047);
; #pragma unroll
;         for (int bj = 0; bj < 2; ++bj) {
;           const int gi = u.pn * 8 + bj * 4 + wc;
;           f32x4 x1 = acc[ai][bj][m][0] * r, x2 = acc[ai][bj][m][1] * r;
;           if (gi % 3 == 2) {
;             const f32x4 cs = *(const GAS f32x4*)(tab + ridx * 32 + 4 * fq), sn = *(const GAS f32x4*)(tab + ridx * 32 + 16 + 4 * fq);
;             const f32x4 o1 = x1 * cs - x2 * sn, o2 = x2 * cs + x1 * sn;
;             x1 = o1; x2 = o2;
;           }
;           GAS u16* rp = dst + (size_t)row * 768 + gi * 32 + 4 * fq;
;           *(GAS u32x2*)(rp) = (u32x2){pk2(x1.x, x1.y), pk2(x1.z, x1.w)};
;           *(GAS u32x2*)(rp + 16) = (u32x2){pk2(x2.x, x2.y), pk2(x2.z, x2.w)};
;         }
.LBB0_322:
	v_mad_i64_i32 v[26:27], s[10:11], v40, s68, v[122:123]
	v_lshl_add_u64 v[40:41], s[36:37], 1, v[26:27]
	v_cvt_pk_bf16_f32 v30, v30, v31
	v_cvt_pk_bf16_f32 v31, v32, v33
	v_mov_b32_e32 v37, v36
	global_store_dwordx2 v[40:41], v[30:31], off
	v_cvt_pk_bf16_f32 v31, v28, v29
	v_mov_b32_e32 v28, v36
	v_mov_b32_e32 v29, v36
	v_cvt_pk_bf16_f32 v30, v38, v39
	v_pk_mul_f32 v[24:25], v[24:25], v[28:29]
	v_pk_mul_f32 v[22:23], v[22:23], v[36:37]
	v_pk_mul_f32 v[20:21], v[20:21], v[28:29]
	s_and_b64 vcc, exec, s[4:5]
	v_pk_mul_f32 v[18:19], v[18:19], v[36:37]
	global_store_dwordx2 v[40:41], v[30:31], off offset:32
	s_cbranch_vccnz .LBB0_324
	s_waitcnt vmcnt(4)
	v_mov_b32_e32 v28, v248
	v_mov_b32_e32 v29, v249
	v_mov_b32_e32 v30, v250
	v_mov_b32_e32 v31, v251
	v_mov_b32_e32 v32, v252
	v_mov_b32_e32 v33, v253
	v_mov_b32_e32 v34, v254
	v_mov_b32_e32 v35, v255
	v_lshl_add_u64 v[246:247], v[246:247], 0, s[96:97]
	global_load_dwordx4 v[248:251], v[246:247], off offset:64
	global_load_dwordx4 v[252:255], v[246:247], off
	v_pk_mul_f32 v[36:37], v[20:21], v[30:31]
	v_pk_mul_f32 v[38:39], v[18:19], v[28:29]
	v_pk_mul_f32 v[30:31], v[24:25], v[30:31]
	v_pk_mul_f32 v[28:29], v[22:23], v[28:29]
	v_pk_fma_f32 v[24:25], v[24:25], v[34:35], v[36:37] neg_lo:[0,0,1] neg_hi:[0,0,1]
	v_pk_fma_f32 v[22:23], v[22:23], v[32:33], v[38:39] neg_lo:[0,0,1] neg_hi:[0,0,1]
	v_pk_fma_f32 v[20:21], v[20:21], v[34:35], v[30:31]
	v_pk_fma_f32 v[18:19], v[18:19], v[32:33], v[28:29]
.LBB0_324:
	v_lshl_add_u64 v[26:27], s[38:39], 1, v[26:27]
	v_cvt_pk_bf16_f32 v22, v22, v23
	v_cvt_pk_bf16_f32 v23, v24, v25
	v_cvt_pk_bf16_f32 v18, v18, v19
	v_cvt_pk_bf16_f32 v19, v20, v21
	global_store_dwordx2 v[26:27], v[22:23], off
	global_store_dwordx2 v[26:27], v[18:19], off offset:32
	v_mov_b32_e32 v18, v244
	s_nop 0
	v_mov_b32_e32 v19, v245
	s_and_b64 vcc, exec, s[6:7]
	v_add_u32_e32 v24, 0xb0, v146
	v_and_b32_e32 v20, 0x7ff, v24
	v_cndmask_b32_e64 v20, v20, v83, s[8:9]
	v_lshlrev_b32_e32 v134, 7, v20
	v_mov_b32_e32 v145, v135
	s_nop 0
	v_add_f32_e32 v18, v18, v19
	v_fmamk_f32 v18, v18, 0x3b2aaaab, v164
	v_mul_f32_e32 v19, 0x4b800000, v18
	v_cmp_gt_f32_e64 s[6:7], s67, v18
	s_nop 1
	v_cndmask_b32_e64 v18, v18, v19, s[6:7]
	v_rsq_f32_e32 v21, v18
	v_lshl_add_u64 v[18:19], s[34:35], 0, v[134:135]
	v_lshl_add_u64 v[18:19], v[18:19], 0, v[144:145]
	v_mul_f32_e32 v20, 0x45800000, v21
	v_cndmask_b32_e64 v20, v21, v20, s[6:7]
	v_mul_f32_e32 v20, 0x3e16c740, v20
	v_pk_mul_f32 v[16:17], v[16:17], v[20:21] op_sel_hi:[1,0]
	v_pk_mul_f32 v[14:15], v[14:15], v[20:21] op_sel_hi:[1,0]
	v_pk_mul_f32 v[12:13], v[12:13], v[20:21] op_sel_hi:[1,0]
	v_pk_mul_f32 v[22:23], v[10:11], v[20:21] op_sel_hi:[1,0]
	s_cbranch_vccnz .LBB0_326
	s_waitcnt vmcnt(4)
	v_mov_b32_e32 v26, v248
	v_mov_b32_e32 v27, v249
	v_mov_b32_e32 v28, v250
	v_mov_b32_e32 v29, v251
	v_mov_b32_e32 v30, v252
	v_mov_b32_e32 v31, v253
	v_mov_b32_e32 v32, v254
	v_mov_b32_e32 v33, v255
	v_pk_mul_f32 v[10:11], v[12:13], v[28:29]
	v_pk_mul_f32 v[34:35], v[22:23], v[26:27]
	v_pk_mul_f32 v[28:29], v[16:17], v[28:29]
	v_pk_mul_f32 v[26:27], v[14:15], v[26:27]
	v_pk_fma_f32 v[16:17], v[16:17], v[32:33], v[10:11] neg_lo:[0,0,1] neg_hi:[0,0,1]
	v_pk_fma_f32 v[14:15], v[14:15], v[30:31], v[34:35] neg_lo:[0,0,1] neg_hi:[0,0,1]
	v_pk_fma_f32 v[12:13], v[12:13], v[32:33], v[28:29]
	v_pk_fma_f32 v[22:23], v[22:23], v[30:31], v[26:27]
.LBB0_326:
	v_mad_i64_i32 v[10:11], s[6:7], v24, s68, v[122:123]
	v_lshl_add_u64 v[24:25], s[36:37], 1, v[10:11]
	v_cvt_pk_bf16_f32 v14, v14, v15
	v_cvt_pk_bf16_f32 v15, v16, v17
	v_mov_b32_e32 v21, v20
	global_store_dwordx2 v[24:25], v[14:15], off
	v_cvt_pk_bf16_f32 v15, v12, v13
	v_mov_b32_e32 v12, v20
	v_mov_b32_e32 v13, v20
	v_cvt_pk_bf16_f32 v14, v22, v23
	v_pk_mul_f32 v[8:9], v[8:9], v[12:13]
	v_pk_mul_f32 v[6:7], v[6:7], v[20:21]
	v_pk_mul_f32 v[4:5], v[4:5], v[12:13]
	s_and_b64 vcc, exec, s[4:5]
	v_pk_mul_f32 v[2:3], v[2:3], v[20:21]
	global_store_dwordx2 v[24:25], v[14:15], off offset:32
	s_cbranch_vccnz .LBB0_283
	s_waitcnt vmcnt(4)
	v_mov_b32_e32 v12, v248
	v_mov_b32_e32 v13, v249
	v_mov_b32_e32 v14, v250
	v_mov_b32_e32 v15, v251
	v_mov_b32_e32 v16, v252
	v_mov_b32_e32 v17, v253
	v_mov_b32_e32 v18, v254
	v_mov_b32_e32 v19, v255
	v_pk_mul_f32 v[20:21], v[4:5], v[14:15]
	v_pk_mul_f32 v[22:23], v[2:3], v[12:13]
	v_pk_mul_f32 v[14:15], v[8:9], v[14:15]
	v_pk_mul_f32 v[12:13], v[6:7], v[12:13]
	v_pk_fma_f32 v[8:9], v[8:9], v[18:19], v[20:21] neg_lo:[0,0,1] neg_hi:[0,0,1]
	v_pk_fma_f32 v[6:7], v[6:7], v[16:17], v[22:23] neg_lo:[0,0,1] neg_hi:[0,0,1]
	v_pk_fma_f32 v[4:5], v[4:5], v[18:19], v[14:15]
	v_pk_fma_f32 v[2:3], v[2:3], v[16:17], v[12:13]
	s_branch .LBB0_283

; #define PHASE(i, call) if (ph_lo <= (i) && (i) < ph_hi) { call; \
;     if (REP_PHASE == (i)) { grid.sync(); if ((i) == 4) { if (blockIdx.x == 0 && threadIdx.x == 0) *(int*)(p.ws + OFF_CTR) = 0; grid.sync(); } call; } \
;     if ((i) + 1 < ph_hi) grid.sync(); }
; __global__ void __launch_bounds__(512) sbmla_fwd(P p, int ph_lo, int ph_hi) {
;   extern __shared__ __attribute__((aligned(16))) char smem[];
;   cg::grid_group grid = cg::this_grid();
;     ...
;   PHASE(0, phase0(p, smem))
;   PHASE(1, phase1(p))
;   PHASE(2, gemm_g1(p, smem))
;   PHASE(3, gemm_g23(p, smem))
;   PHASE(4, attn_phase(p, smem))
;   PHASE(5, gemm_g4(p, smem))
;   PHASE(6, phase_fin(p))
;     ...
; }
	.amdhsa_kernel _Z9sbmla_fwd1Pii
		.amdhsa_group_segment_fixed_size 16
		.amdhsa_private_segment_fixed_size 0
		.amdhsa_kernarg_size 424
		.amdhsa_user_sgpr_count 2
		.amdhsa_user_sgpr_dispatch_ptr 0
		.amdhsa_user_sgpr_queue_ptr 0
		.amdhsa_user_sgpr_kernarg_segment_ptr 1
		.amdhsa_user_sgpr_dispatch_id 0
		.amdhsa_user_sgpr_kernarg_preload_length 0
		.amdhsa_user_sgpr_kernarg_preload_offset 0
		.amdhsa_user_sgpr_private_segment_size 0
		.amdhsa_uses_dynamic_stack 0
		.amdhsa_enable_private_segment 0
		.amdhsa_system_sgpr_workgroup_id_x 1
		.amdhsa_system_sgpr_workgroup_id_y 0
		.amdhsa_system_sgpr_workgroup_id_z 0
		.amdhsa_system_sgpr_workgroup_info 0
		.amdhsa_system_vgpr_workitem_id 2
		.amdhsa_next_free_vgpr 256
		.amdhsa_next_free_sgpr 100
		.amdhsa_accum_offset 256
		.amdhsa_reserve_vcc 1
		.amdhsa_float_round_mode_32 0
		.amdhsa_float_round_mode_16_64 0
		.amdhsa_float_denorm_mode_32 3
		.amdhsa_float_denorm_mode_16_64 3
		.amdhsa_dx10_clamp 1
		.amdhsa_ieee_mode 1
		.amdhsa_fp16_overflow 0
		.amdhsa_tg_split 0
		.amdhsa_exception_fp_ieee_invalid_op 0
		.amdhsa_exception_fp_denorm_src 0
		.amdhsa_exception_fp_ieee_div_zero 0
		.amdhsa_exception_fp_ieee_overflow 0
		.amdhsa_exception_fp_ieee_underflow 0
		.amdhsa_exception_fp_ieee_inexact 0
		.amdhsa_exception_int_div_zero 0
	.end_amdhsa_kernel

; #define PHASE(i, call) if (ph_lo <= (i) && (i) < ph_hi) { call; \
;     if (REP_PHASE == (i)) { grid.sync(); if ((i) == 4) { if (blockIdx.x == 0 && threadIdx.x == 0) *(int*)(p.ws + OFF_CTR) = 0; grid.sync(); } call; } \
;     if ((i) + 1 < ph_hi) grid.sync(); }
; __global__ void __launch_bounds__(512) sbmla_fwd(P p, int ph_lo, int ph_hi) {
;   extern __shared__ __attribute__((aligned(16))) char smem[];
;   cg::grid_group grid = cg::this_grid();
;     ...
;   PHASE(0, phase0(p, smem))
;   PHASE(1, phase1(p))
;   PHASE(2, gemm_g1(p, smem))
;   PHASE(3, gemm_g23(p, smem))
;   PHASE(4, attn_phase(p, smem))
;   PHASE(5, gemm_g4(p, smem))
;   PHASE(6, phase_fin(p))
;     ...
; }
amdhsa.kernels:
  - .agpr_count:     0
    .args:
      - .offset:         0
        .size:           160
        .value_kind:     by_value
      - .offset:         160
        .size:           4
        .value_kind:     by_value
      - .offset:         164
        .size:           4
        .value_kind:     by_value
      - .offset:         168
        .size:           4
        .value_kind:     hidden_block_count_x
      - .offset:         172
        .size:           4
        .value_kind:     hidden_block_count_y
      - .offset:         176
        .size:           4
        .value_kind:     hidden_block_count_z
      - .offset:         180
        .size:           2
        .value_kind:     hidden_group_size_x
      - .offset:         182
        .size:           2
        .value_kind:     hidden_group_size_y
      - .offset:         184
        .size:           2
        .value_kind:     hidden_group_size_z
      - .offset:         186
        .size:           2
        .value_kind:     hidden_remainder_x
      - .offset:         188
        .size:           2
        .value_kind:     hidden_remainder_y
      - .offset:         190
        .size:           2
        .value_kind:     hidden_remainder_z
      - .offset:         208
        .size:           8
        .value_kind:     hidden_global_offset_x
      - .offset:         216
        .size:           8
        .value_kind:     hidden_global_offset_y
      - .offset:         224
        .size:           8
        .value_kind:     hidden_global_offset_z
      - .offset:         232
        .size:           2
        .value_kind:     hidden_grid_dims
      - .offset:         256
        .size:           8
        .value_kind:     hidden_multigrid_sync_arg
      - .offset:         288
        .size:           4
        .value_kind:     hidden_dynamic_lds_size
    .group_segment_fixed_size: 16
    .kernarg_segment_align: 8
    .kernarg_segment_size: 424
    .language:       OpenCL C
    .language_version:
      - 2
      - 0
    .max_flat_workgroup_size: 512
    .name:           _Z9sbmla_fwd1Pii
    .private_segment_fixed_size: 0
    .sgpr_count:     106
    .sgpr_spill_count: 4
    .symbol:         _Z9sbmla_fwd1Pii.kd
    .uniform_work_group_size: 1
    .uses_dynamic_stack: false
    .vgpr_count:     256
    .vgpr_spill_count: 0
    .wavefront_size: 64
